# GEMM K-loops: one static s_setprio 1 for waves 4-7 per loop entry, all per-segment priority toggles replaced by s_nop (recipe 7.4)
# baseline (speedup 1.0000x reference)
.LBB0_295:
	s_ashr_i32 s15, s14, 31
	s_lshl_b64 s[68:69], s[14:15], 20
	s_add_u32 s68, s62, s68
	s_addc_u32 s69, s63, s69
	s_and_b64 s[74:75], s[4:5], exec
	s_cselect_b32 s15, s69, s85
	s_cselect_b32 s77, s68, s84
	s_ashr_i32 s21, s20, 31
	s_lshl_b64 s[74:75], s[20:21], 20
	s_add_u32 s74, s3, s74
	s_addc_u32 s75, s16, s75
	s_and_b64 s[88:89], s[4:5], exec
	s_cselect_b32 s21, s75, s87
	s_cselect_b32 s83, s74, s86
	s_add_u32 s84, s84, 0x80080
	s_addc_u32 s85, s85, 0
	s_add_u32 s90, s86, 0x100
	v_mov_b32_e32 v0, 0
	s_addc_u32 s91, s87, 0
	s_mov_b32 s92, -2
	v_mov_b32_e32 v1, v0
	v_mov_b32_e32 v2, v0
	v_mov_b32_e32 v3, v0
	v_mov_b32_e32 v4, v0
	v_mov_b32_e32 v5, v0
	v_mov_b32_e32 v6, v0
	v_mov_b32_e32 v7, v0
	v_mov_b32_e32 v16, v0
	v_mov_b32_e32 v17, v0
	v_mov_b32_e32 v18, v0
	v_mov_b32_e32 v19, v0
	v_mov_b32_e32 v20, v0
	v_mov_b32_e32 v21, v0
	v_mov_b32_e32 v22, v0
	v_mov_b32_e32 v23, v0
	v_mov_b32_e32 v32, v0
	v_mov_b32_e32 v33, v0
	v_mov_b32_e32 v34, v0
	v_mov_b32_e32 v35, v0
	v_mov_b32_e32 v36, v0
	v_mov_b32_e32 v37, v0
	v_mov_b32_e32 v38, v0
	v_mov_b32_e32 v39, v0
	v_mov_b32_e32 v48, v0
	v_mov_b32_e32 v49, v0
	v_mov_b32_e32 v50, v0
	v_mov_b32_e32 v51, v0
	v_mov_b32_e32 v52, v0
	v_mov_b32_e32 v53, v0
	v_mov_b32_e32 v54, v0
	v_mov_b32_e32 v55, v0
	v_mov_b32_e32 v8, v0
	v_mov_b32_e32 v9, v0
	v_mov_b32_e32 v10, v0
	v_mov_b32_e32 v11, v0
	v_mov_b32_e32 v12, v0
	v_mov_b32_e32 v13, v0
	v_mov_b32_e32 v14, v0
	v_mov_b32_e32 v15, v0
	v_mov_b32_e32 v24, v0
	v_mov_b32_e32 v25, v0
	v_mov_b32_e32 v26, v0
	v_mov_b32_e32 v27, v0
	v_mov_b32_e32 v28, v0
	v_mov_b32_e32 v29, v0
	v_mov_b32_e32 v30, v0
	v_mov_b32_e32 v31, v0
	v_mov_b32_e32 v40, v0
	v_mov_b32_e32 v41, v0
	v_mov_b32_e32 v42, v0
	v_mov_b32_e32 v43, v0
	v_mov_b32_e32 v44, v0
	v_mov_b32_e32 v45, v0
	v_mov_b32_e32 v46, v0
	v_mov_b32_e32 v47, v0
	v_mov_b32_e32 v56, v0
	v_mov_b32_e32 v57, v0
	v_mov_b32_e32 v58, v0
	v_mov_b32_e32 v59, v0
	v_mov_b32_e32 v60, v0
	v_mov_b32_e32 v61, v0
	v_mov_b32_e32 v62, v0
	v_mov_b32_e32 v63, v0
	v_mov_b32_e32 v64, v0
	v_mov_b32_e32 v65, v0
	v_mov_b32_e32 v66, v0
	v_mov_b32_e32 v67, v0
	v_mov_b32_e32 v68, v0
	v_mov_b32_e32 v69, v0
	v_mov_b32_e32 v70, v0
	v_mov_b32_e32 v71, v0
	v_mov_b32_e32 v80, v0
	v_mov_b32_e32 v81, v0
	v_mov_b32_e32 v82, v0
	v_mov_b32_e32 v83, v0
	v_mov_b32_e32 v84, v0
	v_mov_b32_e32 v85, v0
	v_mov_b32_e32 v86, v0
	v_mov_b32_e32 v87, v0
	v_mov_b32_e32 v96, v0
	v_mov_b32_e32 v97, v0
	v_mov_b32_e32 v98, v0
	v_mov_b32_e32 v99, v0
	v_mov_b32_e32 v100, v0
	v_mov_b32_e32 v101, v0
	v_mov_b32_e32 v102, v0
	v_mov_b32_e32 v103, v0
	v_mov_b32_e32 v112, v0
	v_mov_b32_e32 v113, v0
	v_mov_b32_e32 v114, v0
	v_mov_b32_e32 v115, v0
	v_mov_b32_e32 v116, v0
	v_mov_b32_e32 v117, v0
	v_mov_b32_e32 v118, v0
	v_mov_b32_e32 v119, v0
	v_mov_b32_e32 v72, v0
	v_mov_b32_e32 v73, v0
	v_mov_b32_e32 v74, v0
	v_mov_b32_e32 v75, v0
	v_mov_b32_e32 v76, v0
	v_mov_b32_e32 v77, v0
	v_mov_b32_e32 v78, v0
	v_mov_b32_e32 v79, v0
	v_mov_b32_e32 v88, v0
	v_mov_b32_e32 v89, v0
	v_mov_b32_e32 v90, v0
	v_mov_b32_e32 v91, v0
	v_mov_b32_e32 v92, v0
	v_mov_b32_e32 v93, v0
	v_mov_b32_e32 v94, v0
	v_mov_b32_e32 v95, v0
	v_mov_b32_e32 v104, v0
	v_mov_b32_e32 v105, v0
	v_mov_b32_e32 v106, v0
	v_mov_b32_e32 v107, v0
	v_mov_b32_e32 v108, v0
	v_mov_b32_e32 v109, v0
	v_mov_b32_e32 v110, v0
	v_mov_b32_e32 v111, v0
	v_mov_b32_e32 v120, v0
	v_mov_b32_e32 v121, v0
	v_mov_b32_e32 v122, v0
	v_mov_b32_e32 v123, v0
	v_mov_b32_e32 v124, v0
	v_mov_b32_e32 v125, v0
	v_mov_b32_e32 v126, v0
	v_mov_b32_e32 v127, v0
	v_readfirstlane_b32 s99, v184
	s_bitcmp1_b32 s99, 8
	s_cbranch_scc0 .Lprio_296
	s_setprio 1
.Lprio_296:
.LBB0_296:
	ds_read_b128 v[144:147], v151
	ds_read_b128 v[154:157], v151 offset:1024
	ds_read_b128 v[158:161], v151 offset:2048
	ds_read_b128 v[162:165], v151 offset:3072
	ds_read_b128 v[166:169], v152
	ds_read_b128 v[170:173], v152 offset:1024
	ds_read_b128 v[174:177], v152 offset:2048
	ds_read_b128 v[178:181], v152 offset:3072
	s_add_u32 s86, s84, 0xfff80080
	s_addc_u32 s87, s85, -1
	s_cmp_eq_u32 s92, 28
	s_cselect_b32 s89, s15, s87
	s_cselect_b32 s88, s77, s86
	s_cselect_b32 s87, s21, s91
	s_cselect_b32 s86, s83, s90
	v_lshl_add_u64 v[182:183], s[84:85], 0, v[136:137]
	s_add_i32 m0, s18, 0xc000
	ds_read_b128 v[186:189], v153
	ds_read_b128 v[190:193], v153 offset:1024
	ds_read_b128 v[194:197], v153 offset:2048
	ds_read_b128 v[198:201], v153 offset:3072
	ds_read_b128 v[202:205], v153 offset:4096
	ds_read_b128 v[206:209], v153 offset:5120
	ds_read_b128 v[210:213], v153 offset:6144
	ds_read_b128 v[214:217], v153 offset:7168
	global_load_lds_dwordx4 v[182:183], off
	v_lshl_add_u64 v[182:183], s[84:85], 0, v[138:139]
	s_add_i32 m0, s18, 0xe000
	s_nop 0
	global_load_lds_dwordx4 v[182:183], off
	s_waitcnt vmcnt(8)
	s_waitcnt lgkmcnt(0)
	s_barrier
	s_nop 0
	s_waitcnt lgkmcnt(0)
	v_mfma_f32_16x16x32_bf16 v[124:127], v[144:147], v[186:189], v[124:127]
	v_mfma_f32_16x16x32_bf16 v[120:123], v[158:161], v[186:189], v[120:123]
	v_mfma_f32_16x16x32_bf16 v[108:111], v[144:147], v[194:197], v[108:111]
	v_mfma_f32_16x16x32_bf16 v[104:107], v[158:161], v[194:197], v[104:107]
	v_mfma_f32_16x16x32_bf16 v[92:95], v[144:147], v[202:205], v[92:95]
	v_mfma_f32_16x16x32_bf16 v[88:91], v[158:161], v[202:205], v[88:91]
	v_mfma_f32_16x16x32_bf16 v[76:79], v[144:147], v[210:213], v[76:79]
	v_mfma_f32_16x16x32_bf16 v[72:75], v[158:161], v[210:213], v[72:75]
	v_mfma_f32_16x16x32_bf16 v[124:127], v[154:157], v[190:193], v[124:127]
	v_mfma_f32_16x16x32_bf16 v[120:123], v[162:165], v[190:193], v[120:123]
	v_mfma_f32_16x16x32_bf16 v[108:111], v[154:157], v[198:201], v[108:111]
	v_mfma_f32_16x16x32_bf16 v[104:107], v[162:165], v[198:201], v[104:107]
	v_mfma_f32_16x16x32_bf16 v[92:95], v[154:157], v[206:209], v[92:95]
	v_mfma_f32_16x16x32_bf16 v[88:91], v[162:165], v[206:209], v[88:91]
	v_mfma_f32_16x16x32_bf16 v[76:79], v[154:157], v[214:217], v[76:79]
	v_mfma_f32_16x16x32_bf16 v[72:75], v[162:165], v[214:217], v[72:75]
	s_nop 0
	s_nop 0
	v_mfma_f32_16x16x32_bf16 v[116:119], v[166:169], v[186:189], v[116:119]
	v_mfma_f32_16x16x32_bf16 v[112:115], v[174:177], v[186:189], v[112:115]
	v_mfma_f32_16x16x32_bf16 v[100:103], v[166:169], v[194:197], v[100:103]
	v_mfma_f32_16x16x32_bf16 v[96:99], v[174:177], v[194:197], v[96:99]
	v_mfma_f32_16x16x32_bf16 v[84:87], v[166:169], v[202:205], v[84:87]
	v_mfma_f32_16x16x32_bf16 v[80:83], v[174:177], v[202:205], v[80:83]
	v_mfma_f32_16x16x32_bf16 v[68:71], v[166:169], v[210:213], v[68:71]
	v_mfma_f32_16x16x32_bf16 v[64:67], v[174:177], v[210:213], v[64:67]
	v_mfma_f32_16x16x32_bf16 v[116:119], v[170:173], v[190:193], v[116:119]
	v_mfma_f32_16x16x32_bf16 v[112:115], v[178:181], v[190:193], v[112:115]
	v_mfma_f32_16x16x32_bf16 v[100:103], v[170:173], v[198:201], v[100:103]
	v_mfma_f32_16x16x32_bf16 v[96:99], v[178:181], v[198:201], v[96:99]
	v_mfma_f32_16x16x32_bf16 v[84:87], v[170:173], v[206:209], v[84:87]
	v_mfma_f32_16x16x32_bf16 v[80:83], v[178:181], v[206:209], v[80:83]
	v_mfma_f32_16x16x32_bf16 v[68:71], v[170:173], v[214:217], v[68:71]
	v_mfma_f32_16x16x32_bf16 v[64:67], v[178:181], v[214:217], v[64:67]
	s_nop 0
	s_barrier
	s_add_i32 s93, s65, s17
	v_lshl_add_u64 v[182:183], s[86:87], 0, v[130:131]
	s_mov_b32 m0, s93
	ds_read_b128 v[186:189], v153 offset:16384
	ds_read_b128 v[190:193], v153 offset:17408
	ds_read_b128 v[194:197], v153 offset:18432
	ds_read_b128 v[198:201], v153 offset:19456
	ds_read_b128 v[202:205], v153 offset:20480
	ds_read_b128 v[206:209], v153 offset:21504
	ds_read_b128 v[210:213], v153 offset:22528
	ds_read_b128 v[214:217], v153 offset:23552
	global_load_lds_dwordx4 v[182:183], off
	s_add_i32 m0, s93, 0x2000
	s_add_u32 s94, s86, 0x80000
	v_lshl_add_u64 v[218:219], s[86:87], 0, v[134:135]
	s_addc_u32 s95, s87, 0
	s_add_i32 s93, s66, s17
	global_load_lds_dwordx4 v[218:219], off
	v_lshl_add_u64 v[220:221], s[94:95], 0, v[130:131]
	s_mov_b32 m0, s93
	v_lshl_add_u64 v[222:223], s[88:89], 0, v[132:133]
	global_load_lds_dwordx4 v[220:221], off
	v_lshl_add_u64 v[220:221], s[94:95], 0, v[134:135]
	s_add_i32 m0, s93, 0x2000
	s_nop 0
	global_load_lds_dwordx4 v[220:221], off
	v_lshl_add_u64 v[220:221], s[88:89], 0, v[128:129]
	s_mov_b32 m0, s18
	s_nop 0
	global_load_lds_dwordx4 v[220:221], off
	s_mov_b32 m0, s19
	s_nop 0
	global_load_lds_dwordx4 v[222:223], off
	s_waitcnt vmcnt(8)
	s_waitcnt lgkmcnt(0)
	s_barrier
	s_nop 0
	s_waitcnt lgkmcnt(0)
	v_mfma_f32_16x16x32_bf16 v[60:63], v[144:147], v[186:189], v[60:63]
	v_mfma_f32_16x16x32_bf16 v[56:59], v[158:161], v[186:189], v[56:59]
	v_mfma_f32_16x16x32_bf16 v[44:47], v[144:147], v[194:197], v[44:47]
	v_mfma_f32_16x16x32_bf16 v[40:43], v[158:161], v[194:197], v[40:43]
	v_mfma_f32_16x16x32_bf16 v[28:31], v[144:147], v[202:205], v[28:31]
	v_mfma_f32_16x16x32_bf16 v[24:27], v[158:161], v[202:205], v[24:27]
	v_mfma_f32_16x16x32_bf16 v[12:15], v[144:147], v[210:213], v[12:15]
	v_mfma_f32_16x16x32_bf16 v[8:11], v[158:161], v[210:213], v[8:11]
	v_mfma_f32_16x16x32_bf16 v[60:63], v[154:157], v[190:193], v[60:63]
	v_mfma_f32_16x16x32_bf16 v[56:59], v[162:165], v[190:193], v[56:59]
	v_mfma_f32_16x16x32_bf16 v[44:47], v[154:157], v[198:201], v[44:47]
	v_mfma_f32_16x16x32_bf16 v[40:43], v[162:165], v[198:201], v[40:43]
	v_mfma_f32_16x16x32_bf16 v[28:31], v[154:157], v[206:209], v[28:31]
	v_mfma_f32_16x16x32_bf16 v[24:27], v[162:165], v[206:209], v[24:27]
	v_mfma_f32_16x16x32_bf16 v[12:15], v[154:157], v[214:217], v[12:15]
	v_mfma_f32_16x16x32_bf16 v[8:11], v[162:165], v[214:217], v[8:11]
	s_nop 0
	s_nop 0
	v_mfma_f32_16x16x32_bf16 v[52:55], v[166:169], v[186:189], v[52:55]
	v_mfma_f32_16x16x32_bf16 v[48:51], v[174:177], v[186:189], v[48:51]
	v_mfma_f32_16x16x32_bf16 v[36:39], v[166:169], v[194:197], v[36:39]
	v_mfma_f32_16x16x32_bf16 v[32:35], v[174:177], v[194:197], v[32:35]
	v_mfma_f32_16x16x32_bf16 v[20:23], v[166:169], v[202:205], v[20:23]
	v_mfma_f32_16x16x32_bf16 v[16:19], v[174:177], v[202:205], v[16:19]
	v_mfma_f32_16x16x32_bf16 v[4:7], v[166:169], v[210:213], v[4:7]
	v_mfma_f32_16x16x32_bf16 v[0:3], v[174:177], v[210:213], v[0:3]
	v_mfma_f32_16x16x32_bf16 v[52:55], v[170:173], v[190:193], v[52:55]
	v_mfma_f32_16x16x32_bf16 v[48:51], v[178:181], v[190:193], v[48:51]
	v_mfma_f32_16x16x32_bf16 v[36:39], v[170:173], v[198:201], v[36:39]
	v_mfma_f32_16x16x32_bf16 v[32:35], v[178:181], v[198:201], v[32:35]
	v_mfma_f32_16x16x32_bf16 v[20:23], v[170:173], v[206:209], v[20:23]
	v_mfma_f32_16x16x32_bf16 v[16:19], v[178:181], v[206:209], v[16:19]
	v_mfma_f32_16x16x32_bf16 v[4:7], v[170:173], v[214:217], v[4:7]
	v_mfma_f32_16x16x32_bf16 v[0:3], v[178:181], v[214:217], v[0:3]
	s_nop 0
	s_barrier
	s_add_i32 s93, 0, 0x18000
	s_add_i32 s94, 0, 0x1c000
	v_add_u32_e32 v162, s93, v149
	v_add_u32_e32 v178, s94, v149
	ds_read_b128 v[144:147], v162
	ds_read_b128 v[154:157], v162 offset:1024
	ds_read_b128 v[158:161], v162 offset:2048
	ds_read_b128 v[162:165], v162 offset:3072
	ds_read_b128 v[166:169], v178
	ds_read_b128 v[170:173], v178 offset:1024
	ds_read_b128 v[174:177], v178 offset:2048
	ds_read_b128 v[178:181], v178 offset:3072
	s_add_u32 s88, s88, 0x80000
	s_addc_u32 s89, s89, 0
	s_mov_b32 m0, s22
	v_lshl_add_u64 v[224:225], s[88:89], 0, v[128:129]
	ds_read_b128 v[186:189], v153 offset:32768
	ds_read_b128 v[190:193], v153 offset:33792
	ds_read_b128 v[194:197], v153 offset:34816
	ds_read_b128 v[198:201], v153 offset:35840
	ds_read_b128 v[202:205], v153 offset:36864
	ds_read_b128 v[206:209], v153 offset:37888
	ds_read_b128 v[210:213], v153 offset:38912
	ds_read_b128 v[214:217], v153 offset:39936
	global_load_lds_dwordx4 v[224:225], off
	v_lshl_add_u64 v[224:225], s[88:89], 0, v[132:133]
	s_mov_b32 m0, s23
	s_nop 0
	global_load_lds_dwordx4 v[224:225], off
	s_waitcnt vmcnt(8)
	s_waitcnt lgkmcnt(0)
	s_barrier
	s_nop 0
	s_waitcnt lgkmcnt(0)
	v_mfma_f32_16x16x32_bf16 v[124:127], v[144:147], v[186:189], v[124:127]
	v_mfma_f32_16x16x32_bf16 v[120:123], v[158:161], v[186:189], v[120:123]
	v_mfma_f32_16x16x32_bf16 v[108:111], v[144:147], v[194:197], v[108:111]
	v_mfma_f32_16x16x32_bf16 v[104:107], v[158:161], v[194:197], v[104:107]
	v_mfma_f32_16x16x32_bf16 v[92:95], v[144:147], v[202:205], v[92:95]
	v_mfma_f32_16x16x32_bf16 v[88:91], v[158:161], v[202:205], v[88:91]
	v_mfma_f32_16x16x32_bf16 v[76:79], v[144:147], v[210:213], v[76:79]
	v_mfma_f32_16x16x32_bf16 v[72:75], v[158:161], v[210:213], v[72:75]
	v_mfma_f32_16x16x32_bf16 v[124:127], v[154:157], v[190:193], v[124:127]
	v_mfma_f32_16x16x32_bf16 v[120:123], v[162:165], v[190:193], v[120:123]
	v_mfma_f32_16x16x32_bf16 v[108:111], v[154:157], v[198:201], v[108:111]
	v_mfma_f32_16x16x32_bf16 v[104:107], v[162:165], v[198:201], v[104:107]
	v_mfma_f32_16x16x32_bf16 v[92:95], v[154:157], v[206:209], v[92:95]
	v_mfma_f32_16x16x32_bf16 v[88:91], v[162:165], v[206:209], v[88:91]
	v_mfma_f32_16x16x32_bf16 v[76:79], v[154:157], v[214:217], v[76:79]
	v_mfma_f32_16x16x32_bf16 v[72:75], v[162:165], v[214:217], v[72:75]
	s_nop 0
	s_nop 0
	v_mfma_f32_16x16x32_bf16 v[116:119], v[166:169], v[186:189], v[116:119]
	v_mfma_f32_16x16x32_bf16 v[112:115], v[174:177], v[186:189], v[112:115]
	v_mfma_f32_16x16x32_bf16 v[100:103], v[166:169], v[194:197], v[100:103]
	v_mfma_f32_16x16x32_bf16 v[96:99], v[174:177], v[194:197], v[96:99]
	v_mfma_f32_16x16x32_bf16 v[84:87], v[166:169], v[202:205], v[84:87]
	v_mfma_f32_16x16x32_bf16 v[80:83], v[174:177], v[202:205], v[80:83]
	v_mfma_f32_16x16x32_bf16 v[68:71], v[166:169], v[210:213], v[68:71]
	v_mfma_f32_16x16x32_bf16 v[64:67], v[174:177], v[210:213], v[64:67]
	v_mfma_f32_16x16x32_bf16 v[116:119], v[170:173], v[190:193], v[116:119]
	v_mfma_f32_16x16x32_bf16 v[112:115], v[178:181], v[190:193], v[112:115]
	v_mfma_f32_16x16x32_bf16 v[100:103], v[170:173], v[198:201], v[100:103]
	v_mfma_f32_16x16x32_bf16 v[96:99], v[178:181], v[198:201], v[96:99]
	v_mfma_f32_16x16x32_bf16 v[84:87], v[170:173], v[206:209], v[84:87]
	v_mfma_f32_16x16x32_bf16 v[80:83], v[178:181], v[206:209], v[80:83]
	v_mfma_f32_16x16x32_bf16 v[68:71], v[170:173], v[214:217], v[68:71]
	v_mfma_f32_16x16x32_bf16 v[64:67], v[178:181], v[214:217], v[64:67]
	s_nop 0
	s_barrier
	s_add_i32 s88, s93, s17
	v_lshl_add_u64 v[182:183], v[182:183], 0, s[8:9]
	s_mov_b32 m0, s88
	ds_read_b128 v[186:189], v153 offset:49152
	ds_read_b128 v[190:193], v153 offset:50176
	ds_read_b128 v[194:197], v153 offset:51200
	ds_read_b128 v[198:201], v153 offset:52224
	ds_read_b128 v[202:205], v153 offset:53248
	ds_read_b128 v[206:209], v153 offset:54272
	ds_read_b128 v[210:213], v153 offset:55296
	ds_read_b128 v[214:217], v153 offset:56320
	global_load_lds_dwordx4 v[182:183], off
	s_add_i32 m0, s88, 0x2000
	s_add_u32 s86, s86, 0x80080
	v_lshl_add_u64 v[182:183], v[218:219], 0, s[8:9]
	s_addc_u32 s87, s87, 0
	s_add_i32 s88, s94, s17
	global_load_lds_dwordx4 v[182:183], off
	v_lshl_add_u64 v[182:183], s[86:87], 0, v[130:131]
	s_mov_b32 m0, s88
	s_nop 0
	global_load_lds_dwordx4 v[182:183], off
	v_lshl_add_u64 v[182:183], s[86:87], 0, v[134:135]
	s_add_i32 m0, s88, 0x2000
	s_nop 0
	global_load_lds_dwordx4 v[182:183], off
	v_lshl_add_u64 v[182:183], v[220:221], 0, s[8:9]
	s_mov_b32 m0, s25
	s_nop 0
	global_load_lds_dwordx4 v[182:183], off
	v_lshl_add_u64 v[182:183], v[222:223], 0, s[8:9]
	s_mov_b32 m0, s26
	s_nop 0
	global_load_lds_dwordx4 v[182:183], off
	s_waitcnt vmcnt(8)
	s_waitcnt lgkmcnt(0)
	s_barrier
	s_nop 0
	s_waitcnt lgkmcnt(0)
	v_mfma_f32_16x16x32_bf16 v[60:63], v[144:147], v[186:189], v[60:63]
	v_mfma_f32_16x16x32_bf16 v[56:59], v[158:161], v[186:189], v[56:59]
	v_mfma_f32_16x16x32_bf16 v[44:47], v[144:147], v[194:197], v[44:47]
	v_mfma_f32_16x16x32_bf16 v[40:43], v[158:161], v[194:197], v[40:43]
	v_mfma_f32_16x16x32_bf16 v[28:31], v[144:147], v[202:205], v[28:31]
	v_mfma_f32_16x16x32_bf16 v[24:27], v[158:161], v[202:205], v[24:27]
	v_mfma_f32_16x16x32_bf16 v[12:15], v[144:147], v[210:213], v[12:15]
	v_mfma_f32_16x16x32_bf16 v[8:11], v[158:161], v[210:213], v[8:11]
	v_mfma_f32_16x16x32_bf16 v[60:63], v[154:157], v[190:193], v[60:63]
	v_mfma_f32_16x16x32_bf16 v[56:59], v[162:165], v[190:193], v[56:59]
	v_mfma_f32_16x16x32_bf16 v[44:47], v[154:157], v[198:201], v[44:47]
	v_mfma_f32_16x16x32_bf16 v[40:43], v[162:165], v[198:201], v[40:43]
	v_mfma_f32_16x16x32_bf16 v[28:31], v[154:157], v[206:209], v[28:31]
	v_mfma_f32_16x16x32_bf16 v[24:27], v[162:165], v[206:209], v[24:27]
	v_mfma_f32_16x16x32_bf16 v[12:15], v[154:157], v[214:217], v[12:15]
	v_mfma_f32_16x16x32_bf16 v[8:11], v[162:165], v[214:217], v[8:11]
	s_nop 0
	s_nop 0
	v_mfma_f32_16x16x32_bf16 v[52:55], v[166:169], v[186:189], v[52:55]
	v_mfma_f32_16x16x32_bf16 v[48:51], v[174:177], v[186:189], v[48:51]
	v_mfma_f32_16x16x32_bf16 v[36:39], v[166:169], v[194:197], v[36:39]
	v_mfma_f32_16x16x32_bf16 v[32:35], v[174:177], v[194:197], v[32:35]
	v_mfma_f32_16x16x32_bf16 v[20:23], v[166:169], v[202:205], v[20:23]
	v_mfma_f32_16x16x32_bf16 v[16:19], v[174:177], v[202:205], v[16:19]
	v_mfma_f32_16x16x32_bf16 v[4:7], v[166:169], v[210:213], v[4:7]
	v_mfma_f32_16x16x32_bf16 v[0:3], v[174:177], v[210:213], v[0:3]
	v_mfma_f32_16x16x32_bf16 v[52:55], v[170:173], v[190:193], v[52:55]
	v_mfma_f32_16x16x32_bf16 v[48:51], v[178:181], v[190:193], v[48:51]
	v_mfma_f32_16x16x32_bf16 v[36:39], v[170:173], v[198:201], v[36:39]
	v_mfma_f32_16x16x32_bf16 v[32:35], v[178:181], v[198:201], v[32:35]
	v_mfma_f32_16x16x32_bf16 v[20:23], v[170:173], v[206:209], v[20:23]
	v_mfma_f32_16x16x32_bf16 v[16:19], v[178:181], v[206:209], v[16:19]
	v_mfma_f32_16x16x32_bf16 v[4:7], v[170:173], v[214:217], v[4:7]
	v_mfma_f32_16x16x32_bf16 v[0:3], v[178:181], v[214:217], v[0:3]
	s_nop 0
	s_barrier
	s_add_i32 s92, s92, 2
	s_add_u32 s84, s84, 0x100
	s_addc_u32 s85, s85, 0
	s_add_u32 s90, s90, 0x100
	s_addc_u32 s91, s91, 0
	s_cmp_gt_u32 s92, 29
	s_cbranch_scc0 .LBB0_296
	s_setprio 0
	s_nop 0
	s_and_b64 vcc, exec, s[10:11]
	s_cbranch_vccz .LBB0_299
	s_barrier

.LBB0_377:
	s_ashr_i32 s69, s68, 31
	s_lshl_b64 s[74:75], s[68:69], 19
	s_add_u32 s74, s3, s74
	s_addc_u32 s75, s16, s75
	s_and_b64 s[76:77], s[4:5], exec
	s_cselect_b32 s69, s75, s87
	s_cselect_b32 s83, s74, s86
	s_ashr_i32 s21, s20, 31
	s_lshl_b64 s[76:77], s[20:21], 19
	s_add_u32 s76, s17, s76
	s_addc_u32 s77, s18, s77
	s_and_b64 s[90:91], s[4:5], exec
	s_cselect_b32 s21, s77, s89
	s_cselect_b32 s93, s76, s88
	s_add_u32 s86, s86, 0x40080
	s_addc_u32 s87, s87, 0
	s_add_u32 s94, s88, 0x100
	v_mov_b32_e32 v32, 0
	s_addc_u32 s95, s89, 0
	s_mov_b32 s96, -2
	v_mov_b32_e32 v33, v32
	v_mov_b32_e32 v34, v32
	v_mov_b32_e32 v35, v32
	v_mov_b32_e32 v36, v32
	v_mov_b32_e32 v37, v32
	v_mov_b32_e32 v38, v32
	v_mov_b32_e32 v39, v32
	v_mov_b32_e32 v48, v32
	v_mov_b32_e32 v49, v32
	v_mov_b32_e32 v50, v32
	v_mov_b32_e32 v51, v32
	v_mov_b32_e32 v52, v32
	v_mov_b32_e32 v53, v32
	v_mov_b32_e32 v54, v32
	v_mov_b32_e32 v55, v32
	v_mov_b32_e32 v64, v32
	v_mov_b32_e32 v65, v32
	v_mov_b32_e32 v66, v32
	v_mov_b32_e32 v67, v32
	v_mov_b32_e32 v68, v32
	v_mov_b32_e32 v69, v32
	v_mov_b32_e32 v70, v32
	v_mov_b32_e32 v71, v32
	v_mov_b32_e32 v80, v32
	v_mov_b32_e32 v81, v32
	v_mov_b32_e32 v82, v32
	v_mov_b32_e32 v83, v32
	v_mov_b32_e32 v84, v32
	v_mov_b32_e32 v85, v32
	v_mov_b32_e32 v86, v32
	v_mov_b32_e32 v87, v32
	v_mov_b32_e32 v40, v32
	v_mov_b32_e32 v41, v32
	v_mov_b32_e32 v42, v32
	v_mov_b32_e32 v43, v32
	v_mov_b32_e32 v44, v32
	v_mov_b32_e32 v45, v32
	v_mov_b32_e32 v46, v32
	v_mov_b32_e32 v47, v32
	v_mov_b32_e32 v56, v32
	v_mov_b32_e32 v57, v32
	v_mov_b32_e32 v58, v32
	v_mov_b32_e32 v59, v32
	v_mov_b32_e32 v60, v32
	v_mov_b32_e32 v61, v32
	v_mov_b32_e32 v62, v32
	v_mov_b32_e32 v63, v32
	v_mov_b32_e32 v72, v32
	v_mov_b32_e32 v73, v32
	v_mov_b32_e32 v74, v32
	v_mov_b32_e32 v75, v32
	v_mov_b32_e32 v76, v32
	v_mov_b32_e32 v77, v32
	v_mov_b32_e32 v78, v32
	v_mov_b32_e32 v79, v32
	v_mov_b32_e32 v88, v32
	v_mov_b32_e32 v89, v32
	v_mov_b32_e32 v90, v32
	v_mov_b32_e32 v91, v32
	v_mov_b32_e32 v92, v32
	v_mov_b32_e32 v93, v32
	v_mov_b32_e32 v94, v32
	v_mov_b32_e32 v95, v32
	v_mov_b32_e32 v96, v32
	v_mov_b32_e32 v97, v32
	v_mov_b32_e32 v98, v32
	v_mov_b32_e32 v99, v32
	v_mov_b32_e32 v100, v32
	v_mov_b32_e32 v101, v32
	v_mov_b32_e32 v102, v32
	v_mov_b32_e32 v103, v32
	v_mov_b32_e32 v112, v32
	v_mov_b32_e32 v113, v32
	v_mov_b32_e32 v114, v32
	v_mov_b32_e32 v115, v32
	v_mov_b32_e32 v116, v32
	v_mov_b32_e32 v117, v32
	v_mov_b32_e32 v118, v32
	v_mov_b32_e32 v119, v32
	v_mov_b32_e32 v128, v32
	v_mov_b32_e32 v129, v32
	v_mov_b32_e32 v130, v32
	v_mov_b32_e32 v131, v32
	v_mov_b32_e32 v132, v32
	v_mov_b32_e32 v133, v32
	v_mov_b32_e32 v134, v32
	v_mov_b32_e32 v135, v32
	v_mov_b32_e32 v144, v32
	v_mov_b32_e32 v145, v32
	v_mov_b32_e32 v146, v32
	v_mov_b32_e32 v147, v32
	v_mov_b32_e32 v148, v32
	v_mov_b32_e32 v149, v32
	v_mov_b32_e32 v150, v32
	v_mov_b32_e32 v151, v32
	v_mov_b32_e32 v104, v32
	v_mov_b32_e32 v105, v32
	v_mov_b32_e32 v106, v32
	v_mov_b32_e32 v107, v32
	v_mov_b32_e32 v108, v32
	v_mov_b32_e32 v109, v32
	v_mov_b32_e32 v110, v32
	v_mov_b32_e32 v111, v32
	v_mov_b32_e32 v120, v32
	v_mov_b32_e32 v121, v32
	v_mov_b32_e32 v122, v32
	v_mov_b32_e32 v123, v32
	v_mov_b32_e32 v124, v32
	v_mov_b32_e32 v125, v32
	v_mov_b32_e32 v126, v32
	v_mov_b32_e32 v127, v32
	v_mov_b32_e32 v136, v32
	v_mov_b32_e32 v137, v32
	v_mov_b32_e32 v138, v32
	v_mov_b32_e32 v139, v32
	v_mov_b32_e32 v140, v32
	v_mov_b32_e32 v141, v32
	v_mov_b32_e32 v142, v32
	v_mov_b32_e32 v143, v32
	v_mov_b32_e32 v152, v32
	v_mov_b32_e32 v153, v32
	v_mov_b32_e32 v154, v32
	v_mov_b32_e32 v155, v32
	v_mov_b32_e32 v156, v32
	v_mov_b32_e32 v157, v32
	v_mov_b32_e32 v158, v32
	v_mov_b32_e32 v159, v32
	v_readfirstlane_b32 s99, v184
	s_bitcmp1_b32 s99, 8
	s_cbranch_scc0 .Lprio_378
	s_setprio 1
.Lprio_378:
.LBB0_378:
	ds_read_b128 v[16:19], v191
	ds_read_b128 v[20:23], v191 offset:1024
	ds_read_b128 v[24:27], v191 offset:2048
	ds_read_b128 v[28:31], v191 offset:3072
	ds_read_b128 v[0:3], v192
	ds_read_b128 v[4:7], v192 offset:1024
	ds_read_b128 v[8:11], v192 offset:2048
	ds_read_b128 v[12:15], v192 offset:3072
	s_add_u32 s88, s86, 0xfffc0080
	s_addc_u32 s89, s87, -1
	s_cmp_eq_u32 s96, 12
	s_cselect_b32 s91, s69, s89
	s_cselect_b32 s90, s83, s88
	s_cselect_b32 s89, s21, s95
	s_cselect_b32 s88, s93, s94
	v_lshl_add_u64 v[218:219], s[86:87], 0, v[168:169]
	s_add_i32 m0, s22, 0xc000
	ds_read_b128 v[176:179], v193
	ds_read_b128 v[180:183], v193 offset:1024
	ds_read_b128 v[194:197], v193 offset:2048
	ds_read_b128 v[198:201], v193 offset:3072
	ds_read_b128 v[202:205], v193 offset:4096
	ds_read_b128 v[206:209], v193 offset:5120
	ds_read_b128 v[210:213], v193 offset:6144
	ds_read_b128 v[214:217], v193 offset:7168
	global_load_lds_dwordx4 v[218:219], off
	v_lshl_add_u64 v[218:219], s[86:87], 0, v[170:171]
	s_add_i32 m0, s22, 0xe000
	s_nop 0
	global_load_lds_dwordx4 v[218:219], off
	s_waitcnt vmcnt(8)
	s_waitcnt lgkmcnt(0)
	s_barrier
	s_nop 0
	s_waitcnt lgkmcnt(0)
	v_mfma_scale_f32_16x16x128_f8f6f4 v[156:159], v[16:23], v[176:183], v[156:159], v186, v187 op_sel_hi:[0,0,0]
	v_mfma_scale_f32_16x16x128_f8f6f4 v[152:155], v[24:31], v[176:183], v[152:155], v186, v187 op_sel_hi:[0,0,0]
	v_mfma_scale_f32_16x16x128_f8f6f4 v[140:143], v[16:23], v[194:201], v[140:143], v186, v187 op_sel_hi:[0,0,0]
	v_mfma_scale_f32_16x16x128_f8f6f4 v[136:139], v[24:31], v[194:201], v[136:139], v186, v187 op_sel_hi:[0,0,0]
	v_mfma_scale_f32_16x16x128_f8f6f4 v[124:127], v[16:23], v[202:209], v[124:127], v186, v187 op_sel_hi:[0,0,0]
	v_mfma_scale_f32_16x16x128_f8f6f4 v[120:123], v[24:31], v[202:209], v[120:123], v186, v187 op_sel_hi:[0,0,0]
	v_mfma_scale_f32_16x16x128_f8f6f4 v[108:111], v[16:23], v[210:217], v[108:111], v186, v187 op_sel_hi:[0,0,0]
	v_mfma_scale_f32_16x16x128_f8f6f4 v[104:107], v[24:31], v[210:217], v[104:107], v186, v187 op_sel_hi:[0,0,0]
	s_nop 0
	s_nop 0
	v_mfma_scale_f32_16x16x128_f8f6f4 v[148:151], v[0:7], v[176:183], v[148:151], v186, v187 op_sel_hi:[0,0,0]
	v_mfma_scale_f32_16x16x128_f8f6f4 v[144:147], v[8:15], v[176:183], v[144:147], v186, v187 op_sel_hi:[0,0,0]
	v_mfma_scale_f32_16x16x128_f8f6f4 v[132:135], v[0:7], v[194:201], v[132:135], v186, v187 op_sel_hi:[0,0,0]
	v_mfma_scale_f32_16x16x128_f8f6f4 v[128:131], v[8:15], v[194:201], v[128:131], v186, v187 op_sel_hi:[0,0,0]
	v_mfma_scale_f32_16x16x128_f8f6f4 v[116:119], v[0:7], v[202:209], v[116:119], v186, v187 op_sel_hi:[0,0,0]
	v_mfma_scale_f32_16x16x128_f8f6f4 v[112:115], v[8:15], v[202:209], v[112:115], v186, v187 op_sel_hi:[0,0,0]
	v_mfma_scale_f32_16x16x128_f8f6f4 v[100:103], v[0:7], v[210:217], v[100:103], v186, v187 op_sel_hi:[0,0,0]
	v_mfma_scale_f32_16x16x128_f8f6f4 v[96:99], v[8:15], v[210:217], v[96:99], v186, v187 op_sel_hi:[0,0,0]
	s_nop 0
	s_barrier
	s_add_i32 s97, s67, s19
	v_lshl_add_u64 v[176:177], s[88:89], 0, v[162:163]
	s_mov_b32 m0, s97
	ds_read_b128 v[194:197], v193 offset:16384
	ds_read_b128 v[198:201], v193 offset:17408
	ds_read_b128 v[202:205], v193 offset:18432
	ds_read_b128 v[206:209], v193 offset:19456
	ds_read_b128 v[210:213], v193 offset:20480
	ds_read_b128 v[214:217], v193 offset:21504
	ds_read_b128 v[218:221], v193 offset:22528
	ds_read_b128 v[222:225], v193 offset:23552
	global_load_lds_dwordx4 v[176:177], off
	s_add_i32 m0, s97, 0x2000
	s_add_u32 vcc_lo, s88, 0x40000
	v_lshl_add_u64 v[178:179], s[88:89], 0, v[166:167]
	s_addc_u32 vcc_hi, s89, 0
	s_add_i32 s97, s85, s19
	global_load_lds_dwordx4 v[178:179], off
	v_lshl_add_u64 v[180:181], vcc, 0, v[162:163]
	s_mov_b32 m0, s97
	v_lshl_add_u64 v[182:183], s[90:91], 0, v[164:165]
	global_load_lds_dwordx4 v[180:181], off
	v_lshl_add_u64 v[180:181], vcc, 0, v[166:167]
	s_add_i32 m0, s97, 0x2000
	s_nop 0
	global_load_lds_dwordx4 v[180:181], off
	v_lshl_add_u64 v[180:181], s[90:91], 0, v[160:161]
	s_mov_b32 m0, s22
	s_nop 0
	global_load_lds_dwordx4 v[180:181], off
	s_mov_b32 m0, s23
	s_nop 0
	global_load_lds_dwordx4 v[182:183], off
	s_waitcnt vmcnt(8)
	s_waitcnt lgkmcnt(0)
	s_barrier
	s_nop 0
	s_waitcnt lgkmcnt(0)
	v_mfma_scale_f32_16x16x128_f8f6f4 v[92:95], v[16:23], v[194:201], v[92:95], v186, v187 op_sel_hi:[0,0,0]
	v_mfma_scale_f32_16x16x128_f8f6f4 v[88:91], v[24:31], v[194:201], v[88:91], v186, v187 op_sel_hi:[0,0,0]
	v_mfma_scale_f32_16x16x128_f8f6f4 v[76:79], v[16:23], v[202:209], v[76:79], v186, v187 op_sel_hi:[0,0,0]
	v_mfma_scale_f32_16x16x128_f8f6f4 v[72:75], v[24:31], v[202:209], v[72:75], v186, v187 op_sel_hi:[0,0,0]
	v_mfma_scale_f32_16x16x128_f8f6f4 v[60:63], v[16:23], v[210:217], v[60:63], v186, v187 op_sel_hi:[0,0,0]
	v_mfma_scale_f32_16x16x128_f8f6f4 v[56:59], v[24:31], v[210:217], v[56:59], v186, v187 op_sel_hi:[0,0,0]
	v_mfma_scale_f32_16x16x128_f8f6f4 v[44:47], v[16:23], v[218:225], v[44:47], v186, v187 op_sel_hi:[0,0,0]
	v_mfma_scale_f32_16x16x128_f8f6f4 v[40:43], v[24:31], v[218:225], v[40:43], v186, v187 op_sel_hi:[0,0,0]
	s_nop 0
	s_nop 0
	v_mfma_scale_f32_16x16x128_f8f6f4 v[84:87], v[0:7], v[194:201], v[84:87], v186, v187 op_sel_hi:[0,0,0]
	v_mfma_scale_f32_16x16x128_f8f6f4 v[80:83], v[8:15], v[194:201], v[80:83], v186, v187 op_sel_hi:[0,0,0]
	v_mfma_scale_f32_16x16x128_f8f6f4 v[68:71], v[0:7], v[202:209], v[68:71], v186, v187 op_sel_hi:[0,0,0]
	v_mfma_scale_f32_16x16x128_f8f6f4 v[64:67], v[8:15], v[202:209], v[64:67], v186, v187 op_sel_hi:[0,0,0]
	v_mfma_scale_f32_16x16x128_f8f6f4 v[52:55], v[0:7], v[210:217], v[52:55], v186, v187 op_sel_hi:[0,0,0]
	v_mfma_scale_f32_16x16x128_f8f6f4 v[48:51], v[8:15], v[210:217], v[48:51], v186, v187 op_sel_hi:[0,0,0]
	v_mfma_scale_f32_16x16x128_f8f6f4 v[36:39], v[0:7], v[218:225], v[36:39], v186, v187 op_sel_hi:[0,0,0]
	v_mfma_scale_f32_16x16x128_f8f6f4 v[32:35], v[8:15], v[218:225], v[32:35], v186, v187 op_sel_hi:[0,0,0]
	s_nop 0
	s_barrier
	s_add_i32 s97, 0, 0x18000
	s_add_i32 vcc_lo, 0, 0x1c000
	v_add_u32_e32 v12, s97, v189
	v_add_u32_e32 v28, vcc_lo, v189
	ds_read_b128 v[0:3], v12
	ds_read_b128 v[4:7], v12 offset:1024
	ds_read_b128 v[8:11], v12 offset:2048
	ds_read_b128 v[12:15], v12 offset:3072
	ds_read_b128 v[16:19], v28
	ds_read_b128 v[20:23], v28 offset:1024
	ds_read_b128 v[24:27], v28 offset:2048
	ds_read_b128 v[28:31], v28 offset:3072
	s_add_u32 s90, s90, 0x40000
	s_addc_u32 s91, s91, 0
	s_mov_b32 m0, s24
	v_lshl_add_u64 v[226:227], s[90:91], 0, v[160:161]
	ds_read_b128 v[194:197], v193 offset:32768
	ds_read_b128 v[198:201], v193 offset:33792
	ds_read_b128 v[202:205], v193 offset:34816
	ds_read_b128 v[206:209], v193 offset:35840
	ds_read_b128 v[210:213], v193 offset:36864
	ds_read_b128 v[214:217], v193 offset:37888
	ds_read_b128 v[218:221], v193 offset:38912
	ds_read_b128 v[222:225], v193 offset:39936
	global_load_lds_dwordx4 v[226:227], off
	v_lshl_add_u64 v[226:227], s[90:91], 0, v[164:165]
	s_mov_b32 m0, s25
	s_nop 0
	global_load_lds_dwordx4 v[226:227], off
	s_waitcnt vmcnt(8)
	s_waitcnt lgkmcnt(0)
	s_barrier
	s_nop 0
	s_waitcnt lgkmcnt(0)
	v_mfma_scale_f32_16x16x128_f8f6f4 v[156:159], v[0:7], v[194:201], v[156:159], v186, v187 op_sel_hi:[0,0,0]
	v_mfma_scale_f32_16x16x128_f8f6f4 v[152:155], v[8:15], v[194:201], v[152:155], v186, v187 op_sel_hi:[0,0,0]
	v_mfma_scale_f32_16x16x128_f8f6f4 v[140:143], v[0:7], v[202:209], v[140:143], v186, v187 op_sel_hi:[0,0,0]
	v_mfma_scale_f32_16x16x128_f8f6f4 v[136:139], v[8:15], v[202:209], v[136:139], v186, v187 op_sel_hi:[0,0,0]
	v_mfma_scale_f32_16x16x128_f8f6f4 v[124:127], v[0:7], v[210:217], v[124:127], v186, v187 op_sel_hi:[0,0,0]
	v_mfma_scale_f32_16x16x128_f8f6f4 v[120:123], v[8:15], v[210:217], v[120:123], v186, v187 op_sel_hi:[0,0,0]
	v_mfma_scale_f32_16x16x128_f8f6f4 v[108:111], v[0:7], v[218:225], v[108:111], v186, v187 op_sel_hi:[0,0,0]
	v_mfma_scale_f32_16x16x128_f8f6f4 v[104:107], v[8:15], v[218:225], v[104:107], v186, v187 op_sel_hi:[0,0,0]
	s_nop 0
	s_nop 0
	v_mfma_scale_f32_16x16x128_f8f6f4 v[148:151], v[16:23], v[194:201], v[148:151], v186, v187 op_sel_hi:[0,0,0]
	v_mfma_scale_f32_16x16x128_f8f6f4 v[144:147], v[24:31], v[194:201], v[144:147], v186, v187 op_sel_hi:[0,0,0]
	v_mfma_scale_f32_16x16x128_f8f6f4 v[132:135], v[16:23], v[202:209], v[132:135], v186, v187 op_sel_hi:[0,0,0]
	v_mfma_scale_f32_16x16x128_f8f6f4 v[128:131], v[24:31], v[202:209], v[128:131], v186, v187 op_sel_hi:[0,0,0]
	v_mfma_scale_f32_16x16x128_f8f6f4 v[116:119], v[16:23], v[210:217], v[116:119], v186, v187 op_sel_hi:[0,0,0]
	v_mfma_scale_f32_16x16x128_f8f6f4 v[112:115], v[24:31], v[210:217], v[112:115], v186, v187 op_sel_hi:[0,0,0]
	v_mfma_scale_f32_16x16x128_f8f6f4 v[100:103], v[16:23], v[218:225], v[100:103], v186, v187 op_sel_hi:[0,0,0]
	v_mfma_scale_f32_16x16x128_f8f6f4 v[96:99], v[24:31], v[218:225], v[96:99], v186, v187 op_sel_hi:[0,0,0]
	s_nop 0
	s_barrier
	s_add_i32 s90, s97, s19
	v_lshl_add_u64 v[176:177], v[176:177], 0, s[10:11]
	s_mov_b32 m0, s90
	ds_read_b128 v[194:197], v193 offset:49152
	ds_read_b128 v[198:201], v193 offset:50176
	ds_read_b128 v[202:205], v193 offset:51200
	ds_read_b128 v[206:209], v193 offset:52224
	ds_read_b128 v[210:213], v193 offset:53248
	ds_read_b128 v[214:217], v193 offset:54272
	ds_read_b128 v[218:221], v193 offset:55296
	ds_read_b128 v[222:225], v193 offset:56320
	global_load_lds_dwordx4 v[176:177], off
	s_add_i32 m0, s90, 0x2000
	s_add_u32 s88, s88, 0x40080
	v_lshl_add_u64 v[176:177], v[178:179], 0, s[10:11]
	s_addc_u32 s89, s89, 0
	s_add_i32 s90, vcc_lo, s19
	global_load_lds_dwordx4 v[176:177], off
	v_lshl_add_u64 v[176:177], s[88:89], 0, v[162:163]
	s_mov_b32 m0, s90
	s_nop 0
	global_load_lds_dwordx4 v[176:177], off
	v_lshl_add_u64 v[176:177], s[88:89], 0, v[166:167]
	s_add_i32 m0, s90, 0x2000
	s_nop 0
	global_load_lds_dwordx4 v[176:177], off
	v_lshl_add_u64 v[176:177], v[180:181], 0, s[10:11]
	s_mov_b32 m0, s27
	s_nop 0
	global_load_lds_dwordx4 v[176:177], off
	v_lshl_add_u64 v[176:177], v[182:183], 0, s[10:11]
	s_mov_b32 m0, s33
	s_nop 0
	global_load_lds_dwordx4 v[176:177], off
	s_waitcnt vmcnt(8)
	s_waitcnt lgkmcnt(0)
	s_barrier
	s_nop 0
	s_waitcnt lgkmcnt(0)
	v_mfma_scale_f32_16x16x128_f8f6f4 v[92:95], v[0:7], v[194:201], v[92:95], v186, v187 op_sel_hi:[0,0,0]
	v_mfma_scale_f32_16x16x128_f8f6f4 v[88:91], v[8:15], v[194:201], v[88:91], v186, v187 op_sel_hi:[0,0,0]
	v_mfma_scale_f32_16x16x128_f8f6f4 v[76:79], v[0:7], v[202:209], v[76:79], v186, v187 op_sel_hi:[0,0,0]
	v_mfma_scale_f32_16x16x128_f8f6f4 v[72:75], v[8:15], v[202:209], v[72:75], v186, v187 op_sel_hi:[0,0,0]
	v_mfma_scale_f32_16x16x128_f8f6f4 v[60:63], v[0:7], v[210:217], v[60:63], v186, v187 op_sel_hi:[0,0,0]
	v_mfma_scale_f32_16x16x128_f8f6f4 v[56:59], v[8:15], v[210:217], v[56:59], v186, v187 op_sel_hi:[0,0,0]
	v_mfma_scale_f32_16x16x128_f8f6f4 v[44:47], v[0:7], v[218:225], v[44:47], v186, v187 op_sel_hi:[0,0,0]
	v_mfma_scale_f32_16x16x128_f8f6f4 v[40:43], v[8:15], v[218:225], v[40:43], v186, v187 op_sel_hi:[0,0,0]
	s_nop 0
	s_nop 0
	v_mfma_scale_f32_16x16x128_f8f6f4 v[84:87], v[16:23], v[194:201], v[84:87], v186, v187 op_sel_hi:[0,0,0]
	v_mfma_scale_f32_16x16x128_f8f6f4 v[80:83], v[24:31], v[194:201], v[80:83], v186, v187 op_sel_hi:[0,0,0]
	v_mfma_scale_f32_16x16x128_f8f6f4 v[68:71], v[16:23], v[202:209], v[68:71], v186, v187 op_sel_hi:[0,0,0]
	v_mfma_scale_f32_16x16x128_f8f6f4 v[64:67], v[24:31], v[202:209], v[64:67], v186, v187 op_sel_hi:[0,0,0]
	v_mfma_scale_f32_16x16x128_f8f6f4 v[52:55], v[16:23], v[210:217], v[52:55], v186, v187 op_sel_hi:[0,0,0]
	v_mfma_scale_f32_16x16x128_f8f6f4 v[48:51], v[24:31], v[210:217], v[48:51], v186, v187 op_sel_hi:[0,0,0]
	v_mfma_scale_f32_16x16x128_f8f6f4 v[36:39], v[16:23], v[218:225], v[36:39], v186, v187 op_sel_hi:[0,0,0]
	v_mfma_scale_f32_16x16x128_f8f6f4 v[32:35], v[24:31], v[218:225], v[32:35], v186, v187 op_sel_hi:[0,0,0]
	s_nop 0
	s_barrier
	s_add_i32 s96, s96, 2
	s_add_u32 s86, s86, 0x100
	s_addc_u32 s87, s87, 0
	s_add_u32 s94, s94, 0x100
	s_addc_u32 s95, s95, 0
	s_cmp_gt_u32 s96, 13
	s_cbranch_scc0 .LBB0_378
	s_setprio 0
	s_nop 0
	s_and_b64 vcc, exec, s[12:13]
	s_cbranch_vccz .LBB0_381
	s_barrier

.LBB0_871:
	s_ashr_i32 s45, s44, 31
	s_lshl_b64 s[46:47], s[44:45], 19
	s_add_u32 s46, s62, s46
	s_addc_u32 s47, s63, s47
	s_and_b64 s[48:49], s[4:5], exec
	s_cselect_b32 s45, s47, s57
	s_cselect_b32 s53, s46, s56
	s_ashr_i32 s43, s42, 31
	s_lshl_b64 s[48:49], s[42:43], 19
	s_add_u32 s48, s3, s48
	s_addc_u32 s49, s16, s49
	s_and_b64 s[60:61], s[4:5], exec
	s_cselect_b32 s43, s49, s59
	s_cselect_b32 s69, s48, s58
	s_add_u32 s56, s56, 0x40080
	s_addc_u32 s57, s57, 0
	s_add_u32 s70, s58, 0x100
	v_mov_b32_e32 v32, 0
	s_addc_u32 s71, s59, 0
	s_mov_b32 s72, -2
	v_mov_b32_e32 v33, v32
	v_mov_b32_e32 v34, v32
	v_mov_b32_e32 v35, v32
	v_mov_b32_e32 v36, v32
	v_mov_b32_e32 v37, v32
	v_mov_b32_e32 v38, v32
	v_mov_b32_e32 v39, v32
	v_mov_b32_e32 v48, v32
	v_mov_b32_e32 v49, v32
	v_mov_b32_e32 v50, v32
	v_mov_b32_e32 v51, v32
	v_mov_b32_e32 v52, v32
	v_mov_b32_e32 v53, v32
	v_mov_b32_e32 v54, v32
	v_mov_b32_e32 v55, v32
	v_mov_b32_e32 v64, v32
	v_mov_b32_e32 v65, v32
	v_mov_b32_e32 v66, v32
	v_mov_b32_e32 v67, v32
	v_mov_b32_e32 v68, v32
	v_mov_b32_e32 v69, v32
	v_mov_b32_e32 v70, v32
	v_mov_b32_e32 v71, v32
	v_mov_b32_e32 v80, v32
	v_mov_b32_e32 v81, v32
	v_mov_b32_e32 v82, v32
	v_mov_b32_e32 v83, v32
	v_mov_b32_e32 v84, v32
	v_mov_b32_e32 v85, v32
	v_mov_b32_e32 v86, v32
	v_mov_b32_e32 v87, v32
	v_mov_b32_e32 v40, v32
	v_mov_b32_e32 v41, v32
	v_mov_b32_e32 v42, v32
	v_mov_b32_e32 v43, v32
	v_mov_b32_e32 v44, v32
	v_mov_b32_e32 v45, v32
	v_mov_b32_e32 v46, v32
	v_mov_b32_e32 v47, v32
	v_mov_b32_e32 v56, v32
	v_mov_b32_e32 v57, v32
	v_mov_b32_e32 v58, v32
	v_mov_b32_e32 v59, v32
	v_mov_b32_e32 v60, v32
	v_mov_b32_e32 v61, v32
	v_mov_b32_e32 v62, v32
	v_mov_b32_e32 v63, v32
	v_mov_b32_e32 v72, v32
	v_mov_b32_e32 v73, v32
	v_mov_b32_e32 v74, v32
	v_mov_b32_e32 v75, v32
	v_mov_b32_e32 v76, v32
	v_mov_b32_e32 v77, v32
	v_mov_b32_e32 v78, v32
	v_mov_b32_e32 v79, v32
	v_mov_b32_e32 v88, v32
	v_mov_b32_e32 v89, v32
	v_mov_b32_e32 v90, v32
	v_mov_b32_e32 v91, v32
	v_mov_b32_e32 v92, v32
	v_mov_b32_e32 v93, v32
	v_mov_b32_e32 v94, v32
	v_mov_b32_e32 v95, v32
	v_mov_b32_e32 v96, v32
	v_mov_b32_e32 v97, v32
	v_mov_b32_e32 v98, v32
	v_mov_b32_e32 v99, v32
	v_mov_b32_e32 v100, v32
	v_mov_b32_e32 v101, v32
	v_mov_b32_e32 v102, v32
	v_mov_b32_e32 v103, v32
	v_mov_b32_e32 v112, v32
	v_mov_b32_e32 v113, v32
	v_mov_b32_e32 v114, v32
	v_mov_b32_e32 v115, v32
	v_mov_b32_e32 v116, v32
	v_mov_b32_e32 v117, v32
	v_mov_b32_e32 v118, v32
	v_mov_b32_e32 v119, v32
	v_mov_b32_e32 v128, v32
	v_mov_b32_e32 v129, v32
	v_mov_b32_e32 v130, v32
	v_mov_b32_e32 v131, v32
	v_mov_b32_e32 v132, v32
	v_mov_b32_e32 v133, v32
	v_mov_b32_e32 v134, v32
	v_mov_b32_e32 v135, v32
	v_mov_b32_e32 v144, v32
	v_mov_b32_e32 v145, v32
	v_mov_b32_e32 v146, v32
	v_mov_b32_e32 v147, v32
	v_mov_b32_e32 v148, v32
	v_mov_b32_e32 v149, v32
	v_mov_b32_e32 v150, v32
	v_mov_b32_e32 v151, v32
	v_mov_b32_e32 v104, v32
	v_mov_b32_e32 v105, v32
	v_mov_b32_e32 v106, v32
	v_mov_b32_e32 v107, v32
	v_mov_b32_e32 v108, v32
	v_mov_b32_e32 v109, v32
	v_mov_b32_e32 v110, v32
	v_mov_b32_e32 v111, v32
	v_mov_b32_e32 v120, v32
	v_mov_b32_e32 v121, v32
	v_mov_b32_e32 v122, v32
	v_mov_b32_e32 v123, v32
	v_mov_b32_e32 v124, v32
	v_mov_b32_e32 v125, v32
	v_mov_b32_e32 v126, v32
	v_mov_b32_e32 v127, v32
	v_mov_b32_e32 v136, v32
	v_mov_b32_e32 v137, v32
	v_mov_b32_e32 v138, v32
	v_mov_b32_e32 v139, v32
	v_mov_b32_e32 v140, v32
	v_mov_b32_e32 v141, v32
	v_mov_b32_e32 v142, v32
	v_mov_b32_e32 v143, v32
	v_mov_b32_e32 v152, v32
	v_mov_b32_e32 v153, v32
	v_mov_b32_e32 v154, v32
	v_mov_b32_e32 v155, v32
	v_mov_b32_e32 v156, v32
	v_mov_b32_e32 v157, v32
	v_mov_b32_e32 v158, v32
	v_mov_b32_e32 v159, v32
	v_readfirstlane_b32 s78, v184
	s_lshr_b32 s78, s78, 6
	s_lshl_b32 s79, s2, 3
	s_add_u32 s78, s78, s79
	s_lshl_b32 s78, s78, 13
	v_readlane_b32 s80, v254, 10
	v_readlane_b32 s81, v254, 11
	v_readlane_b32 s82, v254, 12
	v_readlane_b32 s83, v254, 13
	s_add_u32 s80, s80, s78
	s_addc_u32 s81, s81, 0
	s_add_u32 s82, s82, s78
	s_addc_u32 s83, s83, 0
	v_mbcnt_hi_u32_b32 v228, -1, v185
	v_lshlrev_b32_e32 v228, 6, v228
	v_readfirstlane_b32 s99, v184
	s_bitcmp1_b32 s99, 8
	s_cbranch_scc0 .Lprio_872
	s_setprio 1
.Lprio_872:
.LBB0_872:
	ds_read_b128 v[16:19], v191
	ds_read_b128 v[20:23], v191 offset:1024
	ds_read_b128 v[24:27], v191 offset:2048
	ds_read_b128 v[28:31], v191 offset:3072
	ds_read_b128 v[0:3], v192
	ds_read_b128 v[4:7], v192 offset:1024
	ds_read_b128 v[8:11], v192 offset:2048
	ds_read_b128 v[12:15], v192 offset:3072
	s_add_u32 s58, s56, 0xfffc0080
	s_addc_u32 s59, s57, -1
	s_cmp_eq_u32 s72, 12
	s_cselect_b32 s61, s45, s59
	s_cselect_b32 s60, s53, s58
	s_cselect_b32 s59, s43, s71
	s_cselect_b32 s58, s69, s70
	v_lshl_add_u64 v[218:219], s[56:57], 0, v[168:169]
	s_add_i32 m0, s18, 0xc000
	ds_read_b128 v[176:179], v193
	ds_read_b128 v[180:183], v193 offset:1024
	ds_read_b128 v[194:197], v193 offset:2048
	ds_read_b128 v[198:201], v193 offset:3072
	ds_read_b128 v[202:205], v193 offset:4096
	ds_read_b128 v[206:209], v193 offset:5120
	ds_read_b128 v[210:213], v193 offset:6144
	ds_read_b128 v[214:217], v193 offset:7168
	global_load_lds_dwordx4 v[218:219], off
	v_lshl_add_u64 v[218:219], s[56:57], 0, v[170:171]
	s_add_i32 m0, s18, 0xe000
	s_nop 0
	global_load_lds_dwordx4 v[218:219], off
	s_waitcnt vmcnt(8)
	s_add_u32 s79, s72, 2
	s_bitcmp1_b32 s79, 3
	s_cselect_b64 s[84:85], s[82:83], s[80:81]
	s_bfe_u32 s86, s79, 0x10002
	s_lshl_b32 s86, s86, 24
	s_bfe_u32 s87, s79, 0x10001
	s_lshl_b32 s87, s87, 12
	s_add_u32 s86, s86, s87
	v_add_u32_e32 v229, s86, v228
	global_load_dword v230, v229, s[84:85]
	s_nop 0
	s_waitcnt lgkmcnt(0)
	s_barrier
	s_nop 0
	s_waitcnt lgkmcnt(0)
	v_mfma_scale_f32_16x16x128_f8f6f4 v[156:159], v[16:23], v[176:183], v[156:159], v186, v187 op_sel_hi:[0,0,0]
	v_mfma_scale_f32_16x16x128_f8f6f4 v[152:155], v[24:31], v[176:183], v[152:155], v186, v187 op_sel_hi:[0,0,0]
	v_mfma_scale_f32_16x16x128_f8f6f4 v[140:143], v[16:23], v[194:201], v[140:143], v186, v187 op_sel_hi:[0,0,0]
	v_mfma_scale_f32_16x16x128_f8f6f4 v[136:139], v[24:31], v[194:201], v[136:139], v186, v187 op_sel_hi:[0,0,0]
	v_mfma_scale_f32_16x16x128_f8f6f4 v[124:127], v[16:23], v[202:209], v[124:127], v186, v187 op_sel_hi:[0,0,0]
	v_mfma_scale_f32_16x16x128_f8f6f4 v[120:123], v[24:31], v[202:209], v[120:123], v186, v187 op_sel_hi:[0,0,0]
	v_mfma_scale_f32_16x16x128_f8f6f4 v[108:111], v[16:23], v[210:217], v[108:111], v186, v187 op_sel_hi:[0,0,0]
	v_mfma_scale_f32_16x16x128_f8f6f4 v[104:107], v[24:31], v[210:217], v[104:107], v186, v187 op_sel_hi:[0,0,0]
	s_nop 0
	s_nop 0
	v_mfma_scale_f32_16x16x128_f8f6f4 v[148:151], v[0:7], v[176:183], v[148:151], v186, v187 op_sel_hi:[0,0,0]
	v_mfma_scale_f32_16x16x128_f8f6f4 v[144:147], v[8:15], v[176:183], v[144:147], v186, v187 op_sel_hi:[0,0,0]
	v_mfma_scale_f32_16x16x128_f8f6f4 v[132:135], v[0:7], v[194:201], v[132:135], v186, v187 op_sel_hi:[0,0,0]
	v_mfma_scale_f32_16x16x128_f8f6f4 v[128:131], v[8:15], v[194:201], v[128:131], v186, v187 op_sel_hi:[0,0,0]
	v_mfma_scale_f32_16x16x128_f8f6f4 v[116:119], v[0:7], v[202:209], v[116:119], v186, v187 op_sel_hi:[0,0,0]
	v_mfma_scale_f32_16x16x128_f8f6f4 v[112:115], v[8:15], v[202:209], v[112:115], v186, v187 op_sel_hi:[0,0,0]
	v_mfma_scale_f32_16x16x128_f8f6f4 v[100:103], v[0:7], v[210:217], v[100:103], v186, v187 op_sel_hi:[0,0,0]
	v_mfma_scale_f32_16x16x128_f8f6f4 v[96:99], v[8:15], v[210:217], v[96:99], v186, v187 op_sel_hi:[0,0,0]
	s_nop 0
	s_barrier
	s_add_i32 s73, s67, s17
	v_lshl_add_u64 v[176:177], s[58:59], 0, v[162:163]
	s_mov_b32 m0, s73
	ds_read_b128 v[194:197], v193 offset:16384
	ds_read_b128 v[198:201], v193 offset:17408
	ds_read_b128 v[202:205], v193 offset:18432
	ds_read_b128 v[206:209], v193 offset:19456
	ds_read_b128 v[210:213], v193 offset:20480
	ds_read_b128 v[214:217], v193 offset:21504
	ds_read_b128 v[218:221], v193 offset:22528
	ds_read_b128 v[222:225], v193 offset:23552
	global_load_lds_dwordx4 v[176:177], off
	s_add_i32 m0, s73, 0x2000
	s_add_u32 s74, s58, 0x40000
	v_lshl_add_u64 v[178:179], s[58:59], 0, v[166:167]
	s_addc_u32 s75, s59, 0
	s_add_i32 s73, s68, s17
	global_load_lds_dwordx4 v[178:179], off
	v_lshl_add_u64 v[180:181], s[74:75], 0, v[162:163]
	s_mov_b32 m0, s73
	v_lshl_add_u64 v[182:183], s[60:61], 0, v[164:165]
	global_load_lds_dwordx4 v[180:181], off
	v_lshl_add_u64 v[180:181], s[74:75], 0, v[166:167]
	s_add_i32 m0, s73, 0x2000
	s_nop 0
	global_load_lds_dwordx4 v[180:181], off
	v_lshl_add_u64 v[180:181], s[60:61], 0, v[160:161]
	s_mov_b32 m0, s18
	s_nop 0
	global_load_lds_dwordx4 v[180:181], off
	s_mov_b32 m0, s19
	s_nop 0
	global_load_lds_dwordx4 v[182:183], off
	s_waitcnt vmcnt(9)
	s_waitcnt lgkmcnt(0)
	s_barrier
	s_nop 0
	s_waitcnt lgkmcnt(0)
	v_mfma_scale_f32_16x16x128_f8f6f4 v[92:95], v[16:23], v[194:201], v[92:95], v186, v187 op_sel_hi:[0,0,0]
	v_mfma_scale_f32_16x16x128_f8f6f4 v[88:91], v[24:31], v[194:201], v[88:91], v186, v187 op_sel_hi:[0,0,0]
	v_mfma_scale_f32_16x16x128_f8f6f4 v[76:79], v[16:23], v[202:209], v[76:79], v186, v187 op_sel_hi:[0,0,0]
	v_mfma_scale_f32_16x16x128_f8f6f4 v[72:75], v[24:31], v[202:209], v[72:75], v186, v187 op_sel_hi:[0,0,0]
	v_mfma_scale_f32_16x16x128_f8f6f4 v[60:63], v[16:23], v[210:217], v[60:63], v186, v187 op_sel_hi:[0,0,0]
	v_mfma_scale_f32_16x16x128_f8f6f4 v[56:59], v[24:31], v[210:217], v[56:59], v186, v187 op_sel_hi:[0,0,0]
	v_mfma_scale_f32_16x16x128_f8f6f4 v[44:47], v[16:23], v[218:225], v[44:47], v186, v187 op_sel_hi:[0,0,0]
	v_mfma_scale_f32_16x16x128_f8f6f4 v[40:43], v[24:31], v[218:225], v[40:43], v186, v187 op_sel_hi:[0,0,0]
	s_nop 0
	s_nop 0
	v_mfma_scale_f32_16x16x128_f8f6f4 v[84:87], v[0:7], v[194:201], v[84:87], v186, v187 op_sel_hi:[0,0,0]
	v_mfma_scale_f32_16x16x128_f8f6f4 v[80:83], v[8:15], v[194:201], v[80:83], v186, v187 op_sel_hi:[0,0,0]
	v_mfma_scale_f32_16x16x128_f8f6f4 v[68:71], v[0:7], v[202:209], v[68:71], v186, v187 op_sel_hi:[0,0,0]
	v_mfma_scale_f32_16x16x128_f8f6f4 v[64:67], v[8:15], v[202:209], v[64:67], v186, v187 op_sel_hi:[0,0,0]
	v_mfma_scale_f32_16x16x128_f8f6f4 v[52:55], v[0:7], v[210:217], v[52:55], v186, v187 op_sel_hi:[0,0,0]
	v_mfma_scale_f32_16x16x128_f8f6f4 v[48:51], v[8:15], v[210:217], v[48:51], v186, v187 op_sel_hi:[0,0,0]
	v_mfma_scale_f32_16x16x128_f8f6f4 v[36:39], v[0:7], v[218:225], v[36:39], v186, v187 op_sel_hi:[0,0,0]
	v_mfma_scale_f32_16x16x128_f8f6f4 v[32:35], v[8:15], v[218:225], v[32:35], v186, v187 op_sel_hi:[0,0,0]
	s_nop 0
	s_barrier
	s_add_i32 s73, 0, 0x18000
	s_add_i32 s74, 0, 0x1c000
	v_add_u32_e32 v12, s73, v189
	v_add_u32_e32 v28, s74, v189
	ds_read_b128 v[0:3], v12
	ds_read_b128 v[4:7], v12 offset:1024
	ds_read_b128 v[8:11], v12 offset:2048
	ds_read_b128 v[12:15], v12 offset:3072
	ds_read_b128 v[16:19], v28
	ds_read_b128 v[20:23], v28 offset:1024
	ds_read_b128 v[24:27], v28 offset:2048
	ds_read_b128 v[28:31], v28 offset:3072
	s_add_u32 s60, s60, 0x40000
	s_addc_u32 s61, s61, 0
	s_mov_b32 m0, s26
	v_lshl_add_u64 v[226:227], s[60:61], 0, v[160:161]
	ds_read_b128 v[194:197], v193 offset:32768
	ds_read_b128 v[198:201], v193 offset:33792
	ds_read_b128 v[202:205], v193 offset:34816
	ds_read_b128 v[206:209], v193 offset:35840
	ds_read_b128 v[210:213], v193 offset:36864
	ds_read_b128 v[214:217], v193 offset:37888
	ds_read_b128 v[218:221], v193 offset:38912
	ds_read_b128 v[222:225], v193 offset:39936
	global_load_lds_dwordx4 v[226:227], off
	v_lshl_add_u64 v[226:227], s[60:61], 0, v[164:165]
	s_mov_b32 m0, s27
	s_nop 0
	global_load_lds_dwordx4 v[226:227], off
	s_waitcnt vmcnt(9)
	s_waitcnt lgkmcnt(0)
	s_barrier
	s_nop 0
	s_waitcnt lgkmcnt(0)
	v_mfma_scale_f32_16x16x128_f8f6f4 v[156:159], v[0:7], v[194:201], v[156:159], v186, v187 op_sel_hi:[0,0,0]
	v_mfma_scale_f32_16x16x128_f8f6f4 v[152:155], v[8:15], v[194:201], v[152:155], v186, v187 op_sel_hi:[0,0,0]
	v_mfma_scale_f32_16x16x128_f8f6f4 v[140:143], v[0:7], v[202:209], v[140:143], v186, v187 op_sel_hi:[0,0,0]
	v_mfma_scale_f32_16x16x128_f8f6f4 v[136:139], v[8:15], v[202:209], v[136:139], v186, v187 op_sel_hi:[0,0,0]
	v_mfma_scale_f32_16x16x128_f8f6f4 v[124:127], v[0:7], v[210:217], v[124:127], v186, v187 op_sel_hi:[0,0,0]
	v_mfma_scale_f32_16x16x128_f8f6f4 v[120:123], v[8:15], v[210:217], v[120:123], v186, v187 op_sel_hi:[0,0,0]
	v_mfma_scale_f32_16x16x128_f8f6f4 v[108:111], v[0:7], v[218:225], v[108:111], v186, v187 op_sel_hi:[0,0,0]
	v_mfma_scale_f32_16x16x128_f8f6f4 v[104:107], v[8:15], v[218:225], v[104:107], v186, v187 op_sel_hi:[0,0,0]
	s_nop 0
	s_nop 0
	v_mfma_scale_f32_16x16x128_f8f6f4 v[148:151], v[16:23], v[194:201], v[148:151], v186, v187 op_sel_hi:[0,0,0]
	v_mfma_scale_f32_16x16x128_f8f6f4 v[144:147], v[24:31], v[194:201], v[144:147], v186, v187 op_sel_hi:[0,0,0]
	v_mfma_scale_f32_16x16x128_f8f6f4 v[132:135], v[16:23], v[202:209], v[132:135], v186, v187 op_sel_hi:[0,0,0]
	v_mfma_scale_f32_16x16x128_f8f6f4 v[128:131], v[24:31], v[202:209], v[128:131], v186, v187 op_sel_hi:[0,0,0]
	v_mfma_scale_f32_16x16x128_f8f6f4 v[116:119], v[16:23], v[210:217], v[116:119], v186, v187 op_sel_hi:[0,0,0]
	v_mfma_scale_f32_16x16x128_f8f6f4 v[112:115], v[24:31], v[210:217], v[112:115], v186, v187 op_sel_hi:[0,0,0]
	v_mfma_scale_f32_16x16x128_f8f6f4 v[100:103], v[16:23], v[218:225], v[100:103], v186, v187 op_sel_hi:[0,0,0]
	v_mfma_scale_f32_16x16x128_f8f6f4 v[96:99], v[24:31], v[218:225], v[96:99], v186, v187 op_sel_hi:[0,0,0]
	s_nop 0
	s_barrier
	s_add_i32 s60, s73, s17
	v_lshl_add_u64 v[176:177], v[176:177], 0, s[10:11]
	s_mov_b32 m0, s60
	ds_read_b128 v[194:197], v193 offset:49152
	ds_read_b128 v[198:201], v193 offset:50176
	ds_read_b128 v[202:205], v193 offset:51200
	ds_read_b128 v[206:209], v193 offset:52224
	ds_read_b128 v[210:213], v193 offset:53248
	ds_read_b128 v[214:217], v193 offset:54272
	ds_read_b128 v[218:221], v193 offset:55296
	ds_read_b128 v[222:225], v193 offset:56320
	global_load_lds_dwordx4 v[176:177], off
	s_add_i32 m0, s60, 0x2000
	s_add_u32 s58, s58, 0x40080
	v_lshl_add_u64 v[176:177], v[178:179], 0, s[10:11]
	s_addc_u32 s59, s59, 0
	s_add_i32 s60, s74, s17
	global_load_lds_dwordx4 v[176:177], off
	v_lshl_add_u64 v[176:177], s[58:59], 0, v[162:163]
	s_mov_b32 m0, s60
	s_nop 0
	global_load_lds_dwordx4 v[176:177], off
	v_lshl_add_u64 v[176:177], s[58:59], 0, v[166:167]
	s_add_i32 m0, s60, 0x2000
	s_nop 0
	global_load_lds_dwordx4 v[176:177], off
	v_lshl_add_u64 v[176:177], v[180:181], 0, s[10:11]
	s_mov_b32 m0, s35
	s_nop 0
	global_load_lds_dwordx4 v[176:177], off
	v_lshl_add_u64 v[176:177], v[182:183], 0, s[10:11]
	s_mov_b32 m0, s55
	s_nop 0
	global_load_lds_dwordx4 v[176:177], off
	s_waitcnt vmcnt(8)
	s_waitcnt lgkmcnt(0)
	s_barrier
	s_nop 0
	s_waitcnt lgkmcnt(0)
	v_mfma_scale_f32_16x16x128_f8f6f4 v[92:95], v[0:7], v[194:201], v[92:95], v186, v187 op_sel_hi:[0,0,0]
	v_mfma_scale_f32_16x16x128_f8f6f4 v[88:91], v[8:15], v[194:201], v[88:91], v186, v187 op_sel_hi:[0,0,0]
	v_mfma_scale_f32_16x16x128_f8f6f4 v[76:79], v[0:7], v[202:209], v[76:79], v186, v187 op_sel_hi:[0,0,0]
	v_mfma_scale_f32_16x16x128_f8f6f4 v[72:75], v[8:15], v[202:209], v[72:75], v186, v187 op_sel_hi:[0,0,0]
	v_mfma_scale_f32_16x16x128_f8f6f4 v[60:63], v[0:7], v[210:217], v[60:63], v186, v187 op_sel_hi:[0,0,0]
	v_mfma_scale_f32_16x16x128_f8f6f4 v[56:59], v[8:15], v[210:217], v[56:59], v186, v187 op_sel_hi:[0,0,0]
	v_mfma_scale_f32_16x16x128_f8f6f4 v[44:47], v[0:7], v[218:225], v[44:47], v186, v187 op_sel_hi:[0,0,0]
	v_mfma_scale_f32_16x16x128_f8f6f4 v[40:43], v[8:15], v[218:225], v[40:43], v186, v187 op_sel_hi:[0,0,0]
	s_nop 0
	s_nop 0
	v_mfma_scale_f32_16x16x128_f8f6f4 v[84:87], v[16:23], v[194:201], v[84:87], v186, v187 op_sel_hi:[0,0,0]
	v_mfma_scale_f32_16x16x128_f8f6f4 v[80:83], v[24:31], v[194:201], v[80:83], v186, v187 op_sel_hi:[0,0,0]
	v_mfma_scale_f32_16x16x128_f8f6f4 v[68:71], v[16:23], v[202:209], v[68:71], v186, v187 op_sel_hi:[0,0,0]
	v_mfma_scale_f32_16x16x128_f8f6f4 v[64:67], v[24:31], v[202:209], v[64:67], v186, v187 op_sel_hi:[0,0,0]
	v_mfma_scale_f32_16x16x128_f8f6f4 v[52:55], v[16:23], v[210:217], v[52:55], v186, v187 op_sel_hi:[0,0,0]
	v_mfma_scale_f32_16x16x128_f8f6f4 v[48:51], v[24:31], v[210:217], v[48:51], v186, v187 op_sel_hi:[0,0,0]
	v_mfma_scale_f32_16x16x128_f8f6f4 v[36:39], v[16:23], v[218:225], v[36:39], v186, v187 op_sel_hi:[0,0,0]
	v_mfma_scale_f32_16x16x128_f8f6f4 v[32:35], v[24:31], v[218:225], v[32:35], v186, v187 op_sel_hi:[0,0,0]
	s_nop 0
	s_barrier
	s_add_i32 s72, s72, 2
	s_add_u32 s56, s56, 0x100
	s_addc_u32 s57, s57, 0
	s_add_u32 s70, s70, 0x100
	s_addc_u32 s71, s71, 0
	s_cmp_gt_u32 s72, 13
	s_cbranch_scc0 .LBB0_872
	s_setprio 0
	s_nop 0
	s_and_b64 vcc, exec, s[12:13]
	s_cbranch_vccz .LBB0_875
	s_barrier

.LBB0_1060:
	s_ashr_i32 s39, s38, 31
	s_lshl_b64 s[40:41], s[38:39], 19
	s_add_u32 s40, s62, s40
	s_addc_u32 s41, s63, s41
	s_and_b64 s[42:43], s[4:5], exec
	s_cselect_b32 s33, s41, s49
	s_cselect_b32 s39, s40, s48
	s_ashr_i32 s37, s36, 31
	s_lshl_b64 s[42:43], s[36:37], 19
	s_add_u32 s42, s3, s42
	s_addc_u32 s43, s16, s43
	s_and_b64 s[54:55], s[4:5], exec
	s_cselect_b32 s37, s43, s53
	s_cselect_b32 s45, s42, s52
	s_add_u32 s48, s48, 0x40080
	s_addc_u32 s49, s49, 0
	s_add_u32 s64, s52, 0x100
	v_mov_b32_e32 v32, 0
	s_addc_u32 s65, s53, 0
	s_mov_b32 s66, -2
	v_mov_b32_e32 v33, v32
	v_mov_b32_e32 v34, v32
	v_mov_b32_e32 v35, v32
	v_mov_b32_e32 v36, v32
	v_mov_b32_e32 v37, v32
	v_mov_b32_e32 v38, v32
	v_mov_b32_e32 v39, v32
	v_mov_b32_e32 v48, v32
	v_mov_b32_e32 v49, v32
	v_mov_b32_e32 v50, v32
	v_mov_b32_e32 v51, v32
	v_mov_b32_e32 v52, v32
	v_mov_b32_e32 v53, v32
	v_mov_b32_e32 v54, v32
	v_mov_b32_e32 v55, v32
	v_mov_b32_e32 v64, v32
	v_mov_b32_e32 v65, v32
	v_mov_b32_e32 v66, v32
	v_mov_b32_e32 v67, v32
	v_mov_b32_e32 v68, v32
	v_mov_b32_e32 v69, v32
	v_mov_b32_e32 v70, v32
	v_mov_b32_e32 v71, v32
	v_mov_b32_e32 v80, v32
	v_mov_b32_e32 v81, v32
	v_mov_b32_e32 v82, v32
	v_mov_b32_e32 v83, v32
	v_mov_b32_e32 v84, v32
	v_mov_b32_e32 v85, v32
	v_mov_b32_e32 v86, v32
	v_mov_b32_e32 v87, v32
	v_mov_b32_e32 v40, v32
	v_mov_b32_e32 v41, v32
	v_mov_b32_e32 v42, v32
	v_mov_b32_e32 v43, v32
	v_mov_b32_e32 v44, v32
	v_mov_b32_e32 v45, v32
	v_mov_b32_e32 v46, v32
	v_mov_b32_e32 v47, v32
	v_mov_b32_e32 v56, v32
	v_mov_b32_e32 v57, v32
	v_mov_b32_e32 v58, v32
	v_mov_b32_e32 v59, v32
	v_mov_b32_e32 v60, v32
	v_mov_b32_e32 v61, v32
	v_mov_b32_e32 v62, v32
	v_mov_b32_e32 v63, v32
	v_mov_b32_e32 v72, v32
	v_mov_b32_e32 v73, v32
	v_mov_b32_e32 v74, v32
	v_mov_b32_e32 v75, v32
	v_mov_b32_e32 v76, v32
	v_mov_b32_e32 v77, v32
	v_mov_b32_e32 v78, v32
	v_mov_b32_e32 v79, v32
	v_mov_b32_e32 v88, v32
	v_mov_b32_e32 v89, v32
	v_mov_b32_e32 v90, v32
	v_mov_b32_e32 v91, v32
	v_mov_b32_e32 v92, v32
	v_mov_b32_e32 v93, v32
	v_mov_b32_e32 v94, v32
	v_mov_b32_e32 v95, v32
	v_mov_b32_e32 v96, v32
	v_mov_b32_e32 v97, v32
	v_mov_b32_e32 v98, v32
	v_mov_b32_e32 v99, v32
	v_mov_b32_e32 v100, v32
	v_mov_b32_e32 v101, v32
	v_mov_b32_e32 v102, v32
	v_mov_b32_e32 v103, v32
	v_mov_b32_e32 v112, v32
	v_mov_b32_e32 v113, v32
	v_mov_b32_e32 v114, v32
	v_mov_b32_e32 v115, v32
	v_mov_b32_e32 v116, v32
	v_mov_b32_e32 v117, v32
	v_mov_b32_e32 v118, v32
	v_mov_b32_e32 v119, v32
	v_mov_b32_e32 v128, v32
	v_mov_b32_e32 v129, v32
	v_mov_b32_e32 v130, v32
	v_mov_b32_e32 v131, v32
	v_mov_b32_e32 v132, v32
	v_mov_b32_e32 v133, v32
	v_mov_b32_e32 v134, v32
	v_mov_b32_e32 v135, v32
	v_mov_b32_e32 v144, v32
	v_mov_b32_e32 v145, v32
	v_mov_b32_e32 v146, v32
	v_mov_b32_e32 v147, v32
	v_mov_b32_e32 v148, v32
	v_mov_b32_e32 v149, v32
	v_mov_b32_e32 v150, v32
	v_mov_b32_e32 v151, v32
	v_mov_b32_e32 v104, v32
	v_mov_b32_e32 v105, v32
	v_mov_b32_e32 v106, v32
	v_mov_b32_e32 v107, v32
	v_mov_b32_e32 v108, v32
	v_mov_b32_e32 v109, v32
	v_mov_b32_e32 v110, v32
	v_mov_b32_e32 v111, v32
	v_mov_b32_e32 v120, v32
	v_mov_b32_e32 v121, v32
	v_mov_b32_e32 v122, v32
	v_mov_b32_e32 v123, v32
	v_mov_b32_e32 v124, v32
	v_mov_b32_e32 v125, v32
	v_mov_b32_e32 v126, v32
	v_mov_b32_e32 v127, v32
	v_mov_b32_e32 v136, v32
	v_mov_b32_e32 v137, v32
	v_mov_b32_e32 v138, v32
	v_mov_b32_e32 v139, v32
	v_mov_b32_e32 v140, v32
	v_mov_b32_e32 v141, v32
	v_mov_b32_e32 v142, v32
	v_mov_b32_e32 v143, v32
	v_mov_b32_e32 v152, v32
	v_mov_b32_e32 v153, v32
	v_mov_b32_e32 v154, v32
	v_mov_b32_e32 v155, v32
	v_mov_b32_e32 v156, v32
	v_mov_b32_e32 v157, v32
	v_mov_b32_e32 v158, v32
	v_mov_b32_e32 v159, v32
	v_readfirstlane_b32 s99, v184
	s_bitcmp1_b32 s99, 8
	s_cbranch_scc0 .Lprio_1061
	s_setprio 1
.Lprio_1061:
.LBB0_1061:
	ds_read_b128 v[16:19], v191
	ds_read_b128 v[20:23], v191 offset:1024
	ds_read_b128 v[24:27], v191 offset:2048
	ds_read_b128 v[28:31], v191 offset:3072
	ds_read_b128 v[0:3], v192
	ds_read_b128 v[4:7], v192 offset:1024
	ds_read_b128 v[8:11], v192 offset:2048
	ds_read_b128 v[12:15], v192 offset:3072
	s_add_u32 s52, s48, 0xfffc0080
	s_addc_u32 s53, s49, -1
	s_cmp_eq_u32 s66, 12
	s_cselect_b32 s55, s33, s53
	s_cselect_b32 s54, s39, s52
	s_cselect_b32 s53, s37, s65
	s_cselect_b32 s52, s45, s64
	v_lshl_add_u64 v[218:219], s[48:49], 0, v[168:169]
	s_add_i32 m0, s18, 0xc000
	ds_read_b128 v[176:179], v193
	ds_read_b128 v[180:183], v193 offset:1024
	ds_read_b128 v[194:197], v193 offset:2048
	ds_read_b128 v[198:201], v193 offset:3072
	ds_read_b128 v[202:205], v193 offset:4096
	ds_read_b128 v[206:209], v193 offset:5120
	ds_read_b128 v[210:213], v193 offset:6144
	ds_read_b128 v[214:217], v193 offset:7168
	global_load_lds_dwordx4 v[218:219], off
	v_lshl_add_u64 v[218:219], s[48:49], 0, v[170:171]
	s_add_i32 m0, s18, 0xe000
	s_nop 0
	global_load_lds_dwordx4 v[218:219], off
	s_waitcnt vmcnt(8)
	s_waitcnt lgkmcnt(0)
	s_barrier
	s_nop 0
	s_waitcnt lgkmcnt(0)
	v_mfma_scale_f32_16x16x128_f8f6f4 v[156:159], v[16:23], v[176:183], v[156:159], v186, v187 op_sel_hi:[0,0,0]
	v_mfma_scale_f32_16x16x128_f8f6f4 v[152:155], v[24:31], v[176:183], v[152:155], v186, v187 op_sel_hi:[0,0,0]
	v_mfma_scale_f32_16x16x128_f8f6f4 v[140:143], v[16:23], v[194:201], v[140:143], v186, v187 op_sel_hi:[0,0,0]
	v_mfma_scale_f32_16x16x128_f8f6f4 v[136:139], v[24:31], v[194:201], v[136:139], v186, v187 op_sel_hi:[0,0,0]
	v_mfma_scale_f32_16x16x128_f8f6f4 v[124:127], v[16:23], v[202:209], v[124:127], v186, v187 op_sel_hi:[0,0,0]
	v_mfma_scale_f32_16x16x128_f8f6f4 v[120:123], v[24:31], v[202:209], v[120:123], v186, v187 op_sel_hi:[0,0,0]
	v_mfma_scale_f32_16x16x128_f8f6f4 v[108:111], v[16:23], v[210:217], v[108:111], v186, v187 op_sel_hi:[0,0,0]
	v_mfma_scale_f32_16x16x128_f8f6f4 v[104:107], v[24:31], v[210:217], v[104:107], v186, v187 op_sel_hi:[0,0,0]
	s_nop 0
	s_nop 0
	v_mfma_scale_f32_16x16x128_f8f6f4 v[148:151], v[0:7], v[176:183], v[148:151], v186, v187 op_sel_hi:[0,0,0]
	v_mfma_scale_f32_16x16x128_f8f6f4 v[144:147], v[8:15], v[176:183], v[144:147], v186, v187 op_sel_hi:[0,0,0]
	v_mfma_scale_f32_16x16x128_f8f6f4 v[132:135], v[0:7], v[194:201], v[132:135], v186, v187 op_sel_hi:[0,0,0]
	v_mfma_scale_f32_16x16x128_f8f6f4 v[128:131], v[8:15], v[194:201], v[128:131], v186, v187 op_sel_hi:[0,0,0]
	v_mfma_scale_f32_16x16x128_f8f6f4 v[116:119], v[0:7], v[202:209], v[116:119], v186, v187 op_sel_hi:[0,0,0]
	v_mfma_scale_f32_16x16x128_f8f6f4 v[112:115], v[8:15], v[202:209], v[112:115], v186, v187 op_sel_hi:[0,0,0]
	v_mfma_scale_f32_16x16x128_f8f6f4 v[100:103], v[0:7], v[210:217], v[100:103], v186, v187 op_sel_hi:[0,0,0]
	v_mfma_scale_f32_16x16x128_f8f6f4 v[96:99], v[8:15], v[210:217], v[96:99], v186, v187 op_sel_hi:[0,0,0]
	s_nop 0
	s_barrier
	s_add_i32 s67, s60, s17
	v_lshl_add_u64 v[176:177], s[52:53], 0, v[162:163]
	s_mov_b32 m0, s67
	ds_read_b128 v[194:197], v193 offset:16384
	ds_read_b128 v[198:201], v193 offset:17408
	ds_read_b128 v[202:205], v193 offset:18432
	ds_read_b128 v[206:209], v193 offset:19456
	ds_read_b128 v[210:213], v193 offset:20480
	ds_read_b128 v[214:217], v193 offset:21504
	ds_read_b128 v[218:221], v193 offset:22528
	ds_read_b128 v[222:225], v193 offset:23552
	global_load_lds_dwordx4 v[176:177], off
	s_add_i32 m0, s67, 0x2000
	s_add_u32 s68, s52, 0x40000
	v_lshl_add_u64 v[178:179], s[52:53], 0, v[166:167]
	s_addc_u32 s69, s53, 0
	s_add_i32 s67, s61, s17
	global_load_lds_dwordx4 v[178:179], off
	v_lshl_add_u64 v[180:181], s[68:69], 0, v[162:163]
	s_mov_b32 m0, s67
	v_lshl_add_u64 v[182:183], s[54:55], 0, v[164:165]
	global_load_lds_dwordx4 v[180:181], off
	v_lshl_add_u64 v[180:181], s[68:69], 0, v[166:167]
	s_add_i32 m0, s67, 0x2000
	s_nop 0
	global_load_lds_dwordx4 v[180:181], off
	v_lshl_add_u64 v[180:181], s[54:55], 0, v[160:161]
	s_mov_b32 m0, s18
	s_nop 0
	global_load_lds_dwordx4 v[180:181], off
	s_mov_b32 m0, s19
	s_nop 0
	global_load_lds_dwordx4 v[182:183], off
	s_waitcnt vmcnt(8)
	s_waitcnt lgkmcnt(0)
	s_barrier
	s_nop 0
	s_waitcnt lgkmcnt(0)
	v_mfma_scale_f32_16x16x128_f8f6f4 v[92:95], v[16:23], v[194:201], v[92:95], v186, v187 op_sel_hi:[0,0,0]
	v_mfma_scale_f32_16x16x128_f8f6f4 v[88:91], v[24:31], v[194:201], v[88:91], v186, v187 op_sel_hi:[0,0,0]
	v_mfma_scale_f32_16x16x128_f8f6f4 v[76:79], v[16:23], v[202:209], v[76:79], v186, v187 op_sel_hi:[0,0,0]
	v_mfma_scale_f32_16x16x128_f8f6f4 v[72:75], v[24:31], v[202:209], v[72:75], v186, v187 op_sel_hi:[0,0,0]
	v_mfma_scale_f32_16x16x128_f8f6f4 v[60:63], v[16:23], v[210:217], v[60:63], v186, v187 op_sel_hi:[0,0,0]
	v_mfma_scale_f32_16x16x128_f8f6f4 v[56:59], v[24:31], v[210:217], v[56:59], v186, v187 op_sel_hi:[0,0,0]
	v_mfma_scale_f32_16x16x128_f8f6f4 v[44:47], v[16:23], v[218:225], v[44:47], v186, v187 op_sel_hi:[0,0,0]
	v_mfma_scale_f32_16x16x128_f8f6f4 v[40:43], v[24:31], v[218:225], v[40:43], v186, v187 op_sel_hi:[0,0,0]
	s_nop 0
	s_nop 0
	v_mfma_scale_f32_16x16x128_f8f6f4 v[84:87], v[0:7], v[194:201], v[84:87], v186, v187 op_sel_hi:[0,0,0]
	v_mfma_scale_f32_16x16x128_f8f6f4 v[80:83], v[8:15], v[194:201], v[80:83], v186, v187 op_sel_hi:[0,0,0]
	v_mfma_scale_f32_16x16x128_f8f6f4 v[68:71], v[0:7], v[202:209], v[68:71], v186, v187 op_sel_hi:[0,0,0]
	v_mfma_scale_f32_16x16x128_f8f6f4 v[64:67], v[8:15], v[202:209], v[64:67], v186, v187 op_sel_hi:[0,0,0]
	v_mfma_scale_f32_16x16x128_f8f6f4 v[52:55], v[0:7], v[210:217], v[52:55], v186, v187 op_sel_hi:[0,0,0]
	v_mfma_scale_f32_16x16x128_f8f6f4 v[48:51], v[8:15], v[210:217], v[48:51], v186, v187 op_sel_hi:[0,0,0]
	v_mfma_scale_f32_16x16x128_f8f6f4 v[36:39], v[0:7], v[218:225], v[36:39], v186, v187 op_sel_hi:[0,0,0]
	v_mfma_scale_f32_16x16x128_f8f6f4 v[32:35], v[8:15], v[218:225], v[32:35], v186, v187 op_sel_hi:[0,0,0]
	s_nop 0
	s_barrier
	s_add_i32 s67, 0, 0x18000
	s_add_i32 s68, 0, 0x1c000
	v_add_u32_e32 v12, s67, v189
	v_add_u32_e32 v28, s68, v189
	ds_read_b128 v[0:3], v12
	ds_read_b128 v[4:7], v12 offset:1024
	ds_read_b128 v[8:11], v12 offset:2048
	ds_read_b128 v[12:15], v12 offset:3072
	ds_read_b128 v[16:19], v28
	ds_read_b128 v[20:23], v28 offset:1024
	ds_read_b128 v[24:27], v28 offset:2048
	ds_read_b128 v[28:31], v28 offset:3072
	s_add_u32 s54, s54, 0x40000
	s_addc_u32 s55, s55, 0
	s_mov_b32 m0, s26
	v_lshl_add_u64 v[226:227], s[54:55], 0, v[160:161]
	ds_read_b128 v[194:197], v193 offset:32768
	ds_read_b128 v[198:201], v193 offset:33792
	ds_read_b128 v[202:205], v193 offset:34816
	ds_read_b128 v[206:209], v193 offset:35840
	ds_read_b128 v[210:213], v193 offset:36864
	ds_read_b128 v[214:217], v193 offset:37888
	ds_read_b128 v[218:221], v193 offset:38912
	ds_read_b128 v[222:225], v193 offset:39936
	global_load_lds_dwordx4 v[226:227], off
	v_lshl_add_u64 v[226:227], s[54:55], 0, v[164:165]
	s_mov_b32 m0, s27
	s_nop 0
	global_load_lds_dwordx4 v[226:227], off
	s_waitcnt vmcnt(8)
	s_waitcnt lgkmcnt(0)
	s_barrier
	s_nop 0
	s_waitcnt lgkmcnt(0)
	v_mfma_scale_f32_16x16x128_f8f6f4 v[156:159], v[0:7], v[194:201], v[156:159], v186, v187 op_sel_hi:[0,0,0]
	v_mfma_scale_f32_16x16x128_f8f6f4 v[152:155], v[8:15], v[194:201], v[152:155], v186, v187 op_sel_hi:[0,0,0]
	v_mfma_scale_f32_16x16x128_f8f6f4 v[140:143], v[0:7], v[202:209], v[140:143], v186, v187 op_sel_hi:[0,0,0]
	v_mfma_scale_f32_16x16x128_f8f6f4 v[136:139], v[8:15], v[202:209], v[136:139], v186, v187 op_sel_hi:[0,0,0]
	v_mfma_scale_f32_16x16x128_f8f6f4 v[124:127], v[0:7], v[210:217], v[124:127], v186, v187 op_sel_hi:[0,0,0]
	v_mfma_scale_f32_16x16x128_f8f6f4 v[120:123], v[8:15], v[210:217], v[120:123], v186, v187 op_sel_hi:[0,0,0]
	v_mfma_scale_f32_16x16x128_f8f6f4 v[108:111], v[0:7], v[218:225], v[108:111], v186, v187 op_sel_hi:[0,0,0]
	v_mfma_scale_f32_16x16x128_f8f6f4 v[104:107], v[8:15], v[218:225], v[104:107], v186, v187 op_sel_hi:[0,0,0]
	s_nop 0
	s_nop 0
	v_mfma_scale_f32_16x16x128_f8f6f4 v[148:151], v[16:23], v[194:201], v[148:151], v186, v187 op_sel_hi:[0,0,0]
	v_mfma_scale_f32_16x16x128_f8f6f4 v[144:147], v[24:31], v[194:201], v[144:147], v186, v187 op_sel_hi:[0,0,0]
	v_mfma_scale_f32_16x16x128_f8f6f4 v[132:135], v[16:23], v[202:209], v[132:135], v186, v187 op_sel_hi:[0,0,0]
	v_mfma_scale_f32_16x16x128_f8f6f4 v[128:131], v[24:31], v[202:209], v[128:131], v186, v187 op_sel_hi:[0,0,0]
	v_mfma_scale_f32_16x16x128_f8f6f4 v[116:119], v[16:23], v[210:217], v[116:119], v186, v187 op_sel_hi:[0,0,0]
	v_mfma_scale_f32_16x16x128_f8f6f4 v[112:115], v[24:31], v[210:217], v[112:115], v186, v187 op_sel_hi:[0,0,0]
	v_mfma_scale_f32_16x16x128_f8f6f4 v[100:103], v[16:23], v[218:225], v[100:103], v186, v187 op_sel_hi:[0,0,0]
	v_mfma_scale_f32_16x16x128_f8f6f4 v[96:99], v[24:31], v[218:225], v[96:99], v186, v187 op_sel_hi:[0,0,0]
	s_nop 0
	s_barrier
	s_add_i32 s54, s67, s17
	v_lshl_add_u64 v[176:177], v[176:177], 0, s[10:11]
	s_mov_b32 m0, s54
	ds_read_b128 v[194:197], v193 offset:49152
	ds_read_b128 v[198:201], v193 offset:50176
	ds_read_b128 v[202:205], v193 offset:51200
	ds_read_b128 v[206:209], v193 offset:52224
	ds_read_b128 v[210:213], v193 offset:53248
	ds_read_b128 v[214:217], v193 offset:54272
	ds_read_b128 v[218:221], v193 offset:55296
	ds_read_b128 v[222:225], v193 offset:56320
	global_load_lds_dwordx4 v[176:177], off
	s_add_i32 m0, s54, 0x2000
	s_add_u32 s52, s52, 0x40080
	v_lshl_add_u64 v[176:177], v[178:179], 0, s[10:11]
	s_addc_u32 s53, s53, 0
	s_add_i32 s54, s68, s17
	global_load_lds_dwordx4 v[176:177], off
	v_lshl_add_u64 v[176:177], s[52:53], 0, v[162:163]
	s_mov_b32 m0, s54
	s_nop 0
	global_load_lds_dwordx4 v[176:177], off
	v_lshl_add_u64 v[176:177], s[52:53], 0, v[166:167]
	s_add_i32 m0, s54, 0x2000
	s_nop 0
	global_load_lds_dwordx4 v[176:177], off
	v_lshl_add_u64 v[176:177], v[180:181], 0, s[10:11]
	s_mov_b32 m0, s47
	s_nop 0
	global_load_lds_dwordx4 v[176:177], off
	v_lshl_add_u64 v[176:177], v[182:183], 0, s[10:11]
	s_mov_b32 m0, s56
	s_nop 0
	global_load_lds_dwordx4 v[176:177], off
	s_waitcnt vmcnt(8)
	s_waitcnt lgkmcnt(0)
	s_barrier
	s_nop 0
	s_waitcnt lgkmcnt(0)
	v_mfma_scale_f32_16x16x128_f8f6f4 v[92:95], v[0:7], v[194:201], v[92:95], v186, v187 op_sel_hi:[0,0,0]
	v_mfma_scale_f32_16x16x128_f8f6f4 v[88:91], v[8:15], v[194:201], v[88:91], v186, v187 op_sel_hi:[0,0,0]
	v_mfma_scale_f32_16x16x128_f8f6f4 v[76:79], v[0:7], v[202:209], v[76:79], v186, v187 op_sel_hi:[0,0,0]
	v_mfma_scale_f32_16x16x128_f8f6f4 v[72:75], v[8:15], v[202:209], v[72:75], v186, v187 op_sel_hi:[0,0,0]
	v_mfma_scale_f32_16x16x128_f8f6f4 v[60:63], v[0:7], v[210:217], v[60:63], v186, v187 op_sel_hi:[0,0,0]
	v_mfma_scale_f32_16x16x128_f8f6f4 v[56:59], v[8:15], v[210:217], v[56:59], v186, v187 op_sel_hi:[0,0,0]
	v_mfma_scale_f32_16x16x128_f8f6f4 v[44:47], v[0:7], v[218:225], v[44:47], v186, v187 op_sel_hi:[0,0,0]
	v_mfma_scale_f32_16x16x128_f8f6f4 v[40:43], v[8:15], v[218:225], v[40:43], v186, v187 op_sel_hi:[0,0,0]
	s_nop 0
	s_nop 0
	v_mfma_scale_f32_16x16x128_f8f6f4 v[84:87], v[16:23], v[194:201], v[84:87], v186, v187 op_sel_hi:[0,0,0]
	v_mfma_scale_f32_16x16x128_f8f6f4 v[80:83], v[24:31], v[194:201], v[80:83], v186, v187 op_sel_hi:[0,0,0]
	v_mfma_scale_f32_16x16x128_f8f6f4 v[68:71], v[16:23], v[202:209], v[68:71], v186, v187 op_sel_hi:[0,0,0]
	v_mfma_scale_f32_16x16x128_f8f6f4 v[64:67], v[24:31], v[202:209], v[64:67], v186, v187 op_sel_hi:[0,0,0]
	v_mfma_scale_f32_16x16x128_f8f6f4 v[52:55], v[16:23], v[210:217], v[52:55], v186, v187 op_sel_hi:[0,0,0]
	v_mfma_scale_f32_16x16x128_f8f6f4 v[48:51], v[24:31], v[210:217], v[48:51], v186, v187 op_sel_hi:[0,0,0]
	v_mfma_scale_f32_16x16x128_f8f6f4 v[36:39], v[16:23], v[218:225], v[36:39], v186, v187 op_sel_hi:[0,0,0]
	v_mfma_scale_f32_16x16x128_f8f6f4 v[32:35], v[24:31], v[218:225], v[32:35], v186, v187 op_sel_hi:[0,0,0]
	s_nop 0
	s_barrier
	s_add_i32 s66, s66, 2
	s_add_u32 s48, s48, 0x100
	s_addc_u32 s49, s49, 0
	s_add_u32 s64, s64, 0x100
	s_addc_u32 s65, s65, 0
	s_cmp_gt_u32 s66, 13
	s_cbranch_scc0 .LBB0_1061
	s_setprio 0
	s_nop 0
	s_and_b64 vcc, exec, s[12:13]
	s_cbranch_vccz .LBB0_1064
	s_barrier

.LBB0_1194:
	s_ashr_i32 s39, s38, 31
	s_lshl_b64 s[40:41], s[38:39], 21
	s_add_u32 s40, s50, s40
	s_addc_u32 s41, s51, s41
	s_and_b64 s[42:43], s[0:1], exec
	s_cselect_b32 s39, s41, s49
	s_cselect_b32 s45, s40, s48
	s_ashr_i32 s37, s36, 31
	s_lshl_b64 s[42:43], s[36:37], 21
	s_add_u32 s42, s3, s42
	s_addc_u32 s43, s16, s43
	s_and_b64 s[54:55], s[0:1], exec
	s_cselect_b32 s37, s43, s53
	s_cselect_b32 s63, s42, s52
	s_add_u32 s48, s48, 0x100080
	s_addc_u32 s49, s49, 0
	s_add_u32 s64, s52, 0x100
	v_mov_b32_e32 v32, 0
	s_addc_u32 s65, s53, 0
	s_mov_b32 s66, -2
	v_mov_b32_e32 v33, v32
	v_mov_b32_e32 v34, v32
	v_mov_b32_e32 v35, v32
	v_mov_b32_e32 v36, v32
	v_mov_b32_e32 v37, v32
	v_mov_b32_e32 v38, v32
	v_mov_b32_e32 v39, v32
	v_mov_b32_e32 v48, v32
	v_mov_b32_e32 v49, v32
	v_mov_b32_e32 v50, v32
	v_mov_b32_e32 v51, v32
	v_mov_b32_e32 v52, v32
	v_mov_b32_e32 v53, v32
	v_mov_b32_e32 v54, v32
	v_mov_b32_e32 v55, v32
	v_mov_b32_e32 v64, v32
	v_mov_b32_e32 v65, v32
	v_mov_b32_e32 v66, v32
	v_mov_b32_e32 v67, v32
	v_mov_b32_e32 v68, v32
	v_mov_b32_e32 v69, v32
	v_mov_b32_e32 v70, v32
	v_mov_b32_e32 v71, v32
	v_mov_b32_e32 v80, v32
	v_mov_b32_e32 v81, v32
	v_mov_b32_e32 v82, v32
	v_mov_b32_e32 v83, v32
	v_mov_b32_e32 v84, v32
	v_mov_b32_e32 v85, v32
	v_mov_b32_e32 v86, v32
	v_mov_b32_e32 v87, v32
	v_mov_b32_e32 v40, v32
	v_mov_b32_e32 v41, v32
	v_mov_b32_e32 v42, v32
	v_mov_b32_e32 v43, v32
	v_mov_b32_e32 v44, v32
	v_mov_b32_e32 v45, v32
	v_mov_b32_e32 v46, v32
	v_mov_b32_e32 v47, v32
	v_mov_b32_e32 v56, v32
	v_mov_b32_e32 v57, v32
	v_mov_b32_e32 v58, v32
	v_mov_b32_e32 v59, v32
	v_mov_b32_e32 v60, v32
	v_mov_b32_e32 v61, v32
	v_mov_b32_e32 v62, v32
	v_mov_b32_e32 v63, v32
	v_mov_b32_e32 v72, v32
	v_mov_b32_e32 v73, v32
	v_mov_b32_e32 v74, v32
	v_mov_b32_e32 v75, v32
	v_mov_b32_e32 v76, v32
	v_mov_b32_e32 v77, v32
	v_mov_b32_e32 v78, v32
	v_mov_b32_e32 v79, v32
	v_mov_b32_e32 v88, v32
	v_mov_b32_e32 v89, v32
	v_mov_b32_e32 v90, v32
	v_mov_b32_e32 v91, v32
	v_mov_b32_e32 v92, v32
	v_mov_b32_e32 v93, v32
	v_mov_b32_e32 v94, v32
	v_mov_b32_e32 v95, v32
	v_mov_b32_e32 v96, v32
	v_mov_b32_e32 v97, v32
	v_mov_b32_e32 v98, v32
	v_mov_b32_e32 v99, v32
	v_mov_b32_e32 v100, v32
	v_mov_b32_e32 v101, v32
	v_mov_b32_e32 v102, v32
	v_mov_b32_e32 v103, v32
	v_mov_b32_e32 v112, v32
	v_mov_b32_e32 v113, v32
	v_mov_b32_e32 v114, v32
	v_mov_b32_e32 v115, v32
	v_mov_b32_e32 v116, v32
	v_mov_b32_e32 v117, v32
	v_mov_b32_e32 v118, v32
	v_mov_b32_e32 v119, v32
	v_mov_b32_e32 v128, v32
	v_mov_b32_e32 v129, v32
	v_mov_b32_e32 v130, v32
	v_mov_b32_e32 v131, v32
	v_mov_b32_e32 v132, v32
	v_mov_b32_e32 v133, v32
	v_mov_b32_e32 v134, v32
	v_mov_b32_e32 v135, v32
	v_mov_b32_e32 v144, v32
	v_mov_b32_e32 v145, v32
	v_mov_b32_e32 v146, v32
	v_mov_b32_e32 v147, v32
	v_mov_b32_e32 v148, v32
	v_mov_b32_e32 v149, v32
	v_mov_b32_e32 v150, v32
	v_mov_b32_e32 v151, v32
	v_mov_b32_e32 v104, v32
	v_mov_b32_e32 v105, v32
	v_mov_b32_e32 v106, v32
	v_mov_b32_e32 v107, v32
	v_mov_b32_e32 v108, v32
	v_mov_b32_e32 v109, v32
	v_mov_b32_e32 v110, v32
	v_mov_b32_e32 v111, v32
	v_mov_b32_e32 v120, v32
	v_mov_b32_e32 v121, v32
	v_mov_b32_e32 v122, v32
	v_mov_b32_e32 v123, v32
	v_mov_b32_e32 v124, v32
	v_mov_b32_e32 v125, v32
	v_mov_b32_e32 v126, v32
	v_mov_b32_e32 v127, v32
	v_mov_b32_e32 v136, v32
	v_mov_b32_e32 v137, v32
	v_mov_b32_e32 v138, v32
	v_mov_b32_e32 v139, v32
	v_mov_b32_e32 v140, v32
	v_mov_b32_e32 v141, v32
	v_mov_b32_e32 v142, v32
	v_mov_b32_e32 v143, v32
	v_mov_b32_e32 v152, v32
	v_mov_b32_e32 v153, v32
	v_mov_b32_e32 v154, v32
	v_mov_b32_e32 v155, v32
	v_mov_b32_e32 v156, v32
	v_mov_b32_e32 v157, v32
	v_mov_b32_e32 v158, v32
	v_mov_b32_e32 v159, v32
	v_readfirstlane_b32 s78, v184
	s_lshr_b32 s78, s78, 6
	s_lshl_b32 s79, s2, 3
	s_add_u32 s78, s78, s79
	s_lshl_b32 s78, s78, 12
	s_add_u32 s80, s28, 0x14900000
	s_addc_u32 s81, s29, 0
	s_add_u32 s80, s80, s78
	s_addc_u32 s81, s81, 0
	v_mbcnt_hi_u32_b32 v228, -1, v185
	v_lshlrev_b32_e32 v228, 3, v228
	s_nop 0
	v_readfirstlane_b32 s99, v184
	s_bitcmp1_b32 s99, 8
	s_cbranch_scc0 .Lprio_1195
	s_setprio 1
.Lprio_1195:
.LBB0_1195:
	ds_read_b128 v[16:19], v191
	ds_read_b128 v[20:23], v191 offset:1024
	ds_read_b128 v[24:27], v191 offset:2048
	ds_read_b128 v[28:31], v191 offset:3072
	ds_read_b128 v[0:3], v192
	ds_read_b128 v[4:7], v192 offset:1024
	ds_read_b128 v[8:11], v192 offset:2048
	ds_read_b128 v[12:15], v192 offset:3072
	s_add_u32 s52, s48, 0xfff00080
	s_addc_u32 s53, s49, -1
	s_cmp_eq_u32 s66, 60
	s_cselect_b32 s55, s39, s53
	s_cselect_b32 s54, s45, s52
	s_cselect_b32 s53, s37, s65
	s_cselect_b32 s52, s63, s64
	v_lshl_add_u64 v[218:219], s[48:49], 0, v[168:169]
	s_add_i32 m0, s26, 0xc000
	ds_read_b128 v[176:179], v193
	ds_read_b128 v[180:183], v193 offset:1024
	ds_read_b128 v[194:197], v193 offset:2048
	ds_read_b128 v[198:201], v193 offset:3072
	ds_read_b128 v[202:205], v193 offset:4096
	ds_read_b128 v[206:209], v193 offset:5120
	ds_read_b128 v[210:213], v193 offset:6144
	ds_read_b128 v[214:217], v193 offset:7168
	global_load_lds_dwordx4 v[218:219], off
	v_lshl_add_u64 v[218:219], s[48:49], 0, v[170:171]
	s_add_i32 m0, s26, 0xe000
	s_nop 0
	global_load_lds_dwordx4 v[218:219], off
	s_waitcnt vmcnt(8)
	s_add_u32 s79, s66, 2
	s_lshr_b32 s86, s79, 4
	s_lshl_b32 s86, s86, 23
	s_and_b32 s87, s79, 15
	s_lshl_b32 s87, s87, 8
	s_add_u32 s86, s86, s87
	v_add_u32_e32 v229, s86, v228
	global_load_dword v230, v229, s[80:81]
	s_nop 0
	s_waitcnt lgkmcnt(0)
	s_barrier
	s_nop 0
	s_waitcnt lgkmcnt(0)
	v_mfma_scale_f32_16x16x128_f8f6f4 v[156:159], v[16:23], v[176:183], v[156:159], v186, v187 op_sel_hi:[0,0,0]
	v_mfma_scale_f32_16x16x128_f8f6f4 v[152:155], v[24:31], v[176:183], v[152:155], v186, v187 op_sel_hi:[0,0,0]
	v_mfma_scale_f32_16x16x128_f8f6f4 v[140:143], v[16:23], v[194:201], v[140:143], v186, v187 op_sel_hi:[0,0,0]
	v_mfma_scale_f32_16x16x128_f8f6f4 v[136:139], v[24:31], v[194:201], v[136:139], v186, v187 op_sel_hi:[0,0,0]
	v_mfma_scale_f32_16x16x128_f8f6f4 v[124:127], v[16:23], v[202:209], v[124:127], v186, v187 op_sel_hi:[0,0,0]
	v_mfma_scale_f32_16x16x128_f8f6f4 v[120:123], v[24:31], v[202:209], v[120:123], v186, v187 op_sel_hi:[0,0,0]
	v_mfma_scale_f32_16x16x128_f8f6f4 v[108:111], v[16:23], v[210:217], v[108:111], v186, v187 op_sel_hi:[0,0,0]
	v_mfma_scale_f32_16x16x128_f8f6f4 v[104:107], v[24:31], v[210:217], v[104:107], v186, v187 op_sel_hi:[0,0,0]
	s_nop 0
	s_nop 0
	v_mfma_scale_f32_16x16x128_f8f6f4 v[148:151], v[0:7], v[176:183], v[148:151], v186, v187 op_sel_hi:[0,0,0]
	v_mfma_scale_f32_16x16x128_f8f6f4 v[144:147], v[8:15], v[176:183], v[144:147], v186, v187 op_sel_hi:[0,0,0]
	v_mfma_scale_f32_16x16x128_f8f6f4 v[132:135], v[0:7], v[194:201], v[132:135], v186, v187 op_sel_hi:[0,0,0]
	v_mfma_scale_f32_16x16x128_f8f6f4 v[128:131], v[8:15], v[194:201], v[128:131], v186, v187 op_sel_hi:[0,0,0]
	v_mfma_scale_f32_16x16x128_f8f6f4 v[116:119], v[0:7], v[202:209], v[116:119], v186, v187 op_sel_hi:[0,0,0]
	v_mfma_scale_f32_16x16x128_f8f6f4 v[112:115], v[8:15], v[202:209], v[112:115], v186, v187 op_sel_hi:[0,0,0]
	v_mfma_scale_f32_16x16x128_f8f6f4 v[100:103], v[0:7], v[210:217], v[100:103], v186, v187 op_sel_hi:[0,0,0]
	v_mfma_scale_f32_16x16x128_f8f6f4 v[96:99], v[8:15], v[210:217], v[96:99], v186, v187 op_sel_hi:[0,0,0]
	s_nop 0
	s_barrier
	s_add_i32 s67, s61, s17
	v_lshl_add_u64 v[176:177], s[52:53], 0, v[162:163]
	s_mov_b32 m0, s67
	ds_read_b128 v[194:197], v193 offset:16384
	ds_read_b128 v[198:201], v193 offset:17408
	ds_read_b128 v[202:205], v193 offset:18432
	ds_read_b128 v[206:209], v193 offset:19456
	ds_read_b128 v[210:213], v193 offset:20480
	ds_read_b128 v[214:217], v193 offset:21504
	ds_read_b128 v[218:221], v193 offset:22528
	ds_read_b128 v[222:225], v193 offset:23552
	global_load_lds_dwordx4 v[176:177], off
	s_add_i32 m0, s67, 0x2000
	s_add_u32 s68, s52, 0x100000
	v_lshl_add_u64 v[178:179], s[52:53], 0, v[166:167]
	s_addc_u32 s69, s53, 0
	s_add_i32 s67, s62, s17
	global_load_lds_dwordx4 v[178:179], off
	v_lshl_add_u64 v[180:181], s[68:69], 0, v[162:163]
	s_mov_b32 m0, s67
	v_lshl_add_u64 v[182:183], s[54:55], 0, v[164:165]
	global_load_lds_dwordx4 v[180:181], off
	v_lshl_add_u64 v[180:181], s[68:69], 0, v[166:167]
	s_add_i32 m0, s67, 0x2000
	s_nop 0
	global_load_lds_dwordx4 v[180:181], off
	v_lshl_add_u64 v[180:181], s[54:55], 0, v[160:161]
	s_mov_b32 m0, s26
	s_nop 0
	global_load_lds_dwordx4 v[180:181], off
	s_mov_b32 m0, s27
	s_nop 0
	global_load_lds_dwordx4 v[182:183], off
	s_waitcnt vmcnt(9)
	s_waitcnt lgkmcnt(0)
	s_barrier
	s_nop 0
	s_waitcnt lgkmcnt(0)
	v_mfma_scale_f32_16x16x128_f8f6f4 v[92:95], v[16:23], v[194:201], v[92:95], v186, v187 op_sel_hi:[0,0,0]
	v_mfma_scale_f32_16x16x128_f8f6f4 v[88:91], v[24:31], v[194:201], v[88:91], v186, v187 op_sel_hi:[0,0,0]
	v_mfma_scale_f32_16x16x128_f8f6f4 v[76:79], v[16:23], v[202:209], v[76:79], v186, v187 op_sel_hi:[0,0,0]
	v_mfma_scale_f32_16x16x128_f8f6f4 v[72:75], v[24:31], v[202:209], v[72:75], v186, v187 op_sel_hi:[0,0,0]
	v_mfma_scale_f32_16x16x128_f8f6f4 v[60:63], v[16:23], v[210:217], v[60:63], v186, v187 op_sel_hi:[0,0,0]
	v_mfma_scale_f32_16x16x128_f8f6f4 v[56:59], v[24:31], v[210:217], v[56:59], v186, v187 op_sel_hi:[0,0,0]
	v_mfma_scale_f32_16x16x128_f8f6f4 v[44:47], v[16:23], v[218:225], v[44:47], v186, v187 op_sel_hi:[0,0,0]
	v_mfma_scale_f32_16x16x128_f8f6f4 v[40:43], v[24:31], v[218:225], v[40:43], v186, v187 op_sel_hi:[0,0,0]
	s_nop 0
	s_nop 0
	v_mfma_scale_f32_16x16x128_f8f6f4 v[84:87], v[0:7], v[194:201], v[84:87], v186, v187 op_sel_hi:[0,0,0]
	v_mfma_scale_f32_16x16x128_f8f6f4 v[80:83], v[8:15], v[194:201], v[80:83], v186, v187 op_sel_hi:[0,0,0]
	v_mfma_scale_f32_16x16x128_f8f6f4 v[68:71], v[0:7], v[202:209], v[68:71], v186, v187 op_sel_hi:[0,0,0]
	v_mfma_scale_f32_16x16x128_f8f6f4 v[64:67], v[8:15], v[202:209], v[64:67], v186, v187 op_sel_hi:[0,0,0]
	v_mfma_scale_f32_16x16x128_f8f6f4 v[52:55], v[0:7], v[210:217], v[52:55], v186, v187 op_sel_hi:[0,0,0]
	v_mfma_scale_f32_16x16x128_f8f6f4 v[48:51], v[8:15], v[210:217], v[48:51], v186, v187 op_sel_hi:[0,0,0]
	v_mfma_scale_f32_16x16x128_f8f6f4 v[36:39], v[0:7], v[218:225], v[36:39], v186, v187 op_sel_hi:[0,0,0]
	v_mfma_scale_f32_16x16x128_f8f6f4 v[32:35], v[8:15], v[218:225], v[32:35], v186, v187 op_sel_hi:[0,0,0]
	s_nop 0
	s_barrier
	s_add_i32 s67, 0, 0x18000
	s_add_i32 s68, 0, 0x1c000
	v_add_u32_e32 v12, s67, v189
	v_add_u32_e32 v28, s68, v189
	ds_read_b128 v[0:3], v12
	ds_read_b128 v[4:7], v12 offset:1024
	ds_read_b128 v[8:11], v12 offset:2048
	ds_read_b128 v[12:15], v12 offset:3072
	ds_read_b128 v[16:19], v28
	ds_read_b128 v[20:23], v28 offset:1024
	ds_read_b128 v[24:27], v28 offset:2048
	ds_read_b128 v[28:31], v28 offset:3072
	s_add_u32 s54, s54, 0x100000
	s_addc_u32 s55, s55, 0
	s_mov_b32 m0, s33
	v_lshl_add_u64 v[226:227], s[54:55], 0, v[160:161]
	ds_read_b128 v[194:197], v193 offset:32768
	ds_read_b128 v[198:201], v193 offset:33792
	ds_read_b128 v[202:205], v193 offset:34816
	ds_read_b128 v[206:209], v193 offset:35840
	ds_read_b128 v[210:213], v193 offset:36864
	ds_read_b128 v[214:217], v193 offset:37888
	ds_read_b128 v[218:221], v193 offset:38912
	ds_read_b128 v[222:225], v193 offset:39936
	global_load_lds_dwordx4 v[226:227], off
	v_lshl_add_u64 v[226:227], s[54:55], 0, v[164:165]
	s_mov_b32 m0, s35
	s_nop 0
	global_load_lds_dwordx4 v[226:227], off
	s_waitcnt vmcnt(9)
	s_waitcnt lgkmcnt(0)
	s_barrier
	s_nop 0
	s_waitcnt lgkmcnt(0)
	v_mfma_scale_f32_16x16x128_f8f6f4 v[156:159], v[0:7], v[194:201], v[156:159], v186, v187 op_sel_hi:[0,0,0]
	v_mfma_scale_f32_16x16x128_f8f6f4 v[152:155], v[8:15], v[194:201], v[152:155], v186, v187 op_sel_hi:[0,0,0]
	v_mfma_scale_f32_16x16x128_f8f6f4 v[140:143], v[0:7], v[202:209], v[140:143], v186, v187 op_sel_hi:[0,0,0]
	v_mfma_scale_f32_16x16x128_f8f6f4 v[136:139], v[8:15], v[202:209], v[136:139], v186, v187 op_sel_hi:[0,0,0]
	v_mfma_scale_f32_16x16x128_f8f6f4 v[124:127], v[0:7], v[210:217], v[124:127], v186, v187 op_sel_hi:[0,0,0]
	v_mfma_scale_f32_16x16x128_f8f6f4 v[120:123], v[8:15], v[210:217], v[120:123], v186, v187 op_sel_hi:[0,0,0]
	v_mfma_scale_f32_16x16x128_f8f6f4 v[108:111], v[0:7], v[218:225], v[108:111], v186, v187 op_sel_hi:[0,0,0]
	v_mfma_scale_f32_16x16x128_f8f6f4 v[104:107], v[8:15], v[218:225], v[104:107], v186, v187 op_sel_hi:[0,0,0]
	s_nop 0
	s_nop 0
	v_mfma_scale_f32_16x16x128_f8f6f4 v[148:151], v[16:23], v[194:201], v[148:151], v186, v187 op_sel_hi:[0,0,0]
	v_mfma_scale_f32_16x16x128_f8f6f4 v[144:147], v[24:31], v[194:201], v[144:147], v186, v187 op_sel_hi:[0,0,0]
	v_mfma_scale_f32_16x16x128_f8f6f4 v[132:135], v[16:23], v[202:209], v[132:135], v186, v187 op_sel_hi:[0,0,0]
	v_mfma_scale_f32_16x16x128_f8f6f4 v[128:131], v[24:31], v[202:209], v[128:131], v186, v187 op_sel_hi:[0,0,0]
	v_mfma_scale_f32_16x16x128_f8f6f4 v[116:119], v[16:23], v[210:217], v[116:119], v186, v187 op_sel_hi:[0,0,0]
	v_mfma_scale_f32_16x16x128_f8f6f4 v[112:115], v[24:31], v[210:217], v[112:115], v186, v187 op_sel_hi:[0,0,0]
	v_mfma_scale_f32_16x16x128_f8f6f4 v[100:103], v[16:23], v[218:225], v[100:103], v186, v187 op_sel_hi:[0,0,0]
	v_mfma_scale_f32_16x16x128_f8f6f4 v[96:99], v[24:31], v[218:225], v[96:99], v186, v187 op_sel_hi:[0,0,0]
	s_nop 0
	s_barrier
	s_add_i32 s54, s67, s17
	v_lshl_add_u64 v[176:177], v[176:177], 0, s[10:11]
	s_mov_b32 m0, s54
	ds_read_b128 v[194:197], v193 offset:49152
	ds_read_b128 v[198:201], v193 offset:50176
	ds_read_b128 v[202:205], v193 offset:51200
	ds_read_b128 v[206:209], v193 offset:52224
	ds_read_b128 v[210:213], v193 offset:53248
	ds_read_b128 v[214:217], v193 offset:54272
	ds_read_b128 v[218:221], v193 offset:55296
	ds_read_b128 v[222:225], v193 offset:56320
	global_load_lds_dwordx4 v[176:177], off
	s_add_i32 m0, s54, 0x2000
	s_add_u32 s52, s52, 0x100080
	v_lshl_add_u64 v[176:177], v[178:179], 0, s[10:11]
	s_addc_u32 s53, s53, 0
	s_add_i32 s54, s68, s17
	global_load_lds_dwordx4 v[176:177], off
	v_lshl_add_u64 v[176:177], s[52:53], 0, v[162:163]
	s_mov_b32 m0, s54
	s_nop 0
	global_load_lds_dwordx4 v[176:177], off
	v_lshl_add_u64 v[176:177], s[52:53], 0, v[166:167]
	s_add_i32 m0, s54, 0x2000
	s_nop 0
	global_load_lds_dwordx4 v[176:177], off
	v_lshl_add_u64 v[176:177], v[180:181], 0, s[10:11]
	s_mov_b32 m0, s56
	s_nop 0
	global_load_lds_dwordx4 v[176:177], off
	v_lshl_add_u64 v[176:177], v[182:183], 0, s[10:11]
	s_mov_b32 m0, s57
	s_nop 0
	global_load_lds_dwordx4 v[176:177], off
	s_waitcnt vmcnt(8)
	s_waitcnt lgkmcnt(0)
	s_barrier
	s_nop 0
	s_waitcnt lgkmcnt(0)
	v_mfma_scale_f32_16x16x128_f8f6f4 v[92:95], v[0:7], v[194:201], v[92:95], v186, v187 op_sel_hi:[0,0,0]
	v_mfma_scale_f32_16x16x128_f8f6f4 v[88:91], v[8:15], v[194:201], v[88:91], v186, v187 op_sel_hi:[0,0,0]
	v_mfma_scale_f32_16x16x128_f8f6f4 v[76:79], v[0:7], v[202:209], v[76:79], v186, v187 op_sel_hi:[0,0,0]
	v_mfma_scale_f32_16x16x128_f8f6f4 v[72:75], v[8:15], v[202:209], v[72:75], v186, v187 op_sel_hi:[0,0,0]
	v_mfma_scale_f32_16x16x128_f8f6f4 v[60:63], v[0:7], v[210:217], v[60:63], v186, v187 op_sel_hi:[0,0,0]
	v_mfma_scale_f32_16x16x128_f8f6f4 v[56:59], v[8:15], v[210:217], v[56:59], v186, v187 op_sel_hi:[0,0,0]
	v_mfma_scale_f32_16x16x128_f8f6f4 v[44:47], v[0:7], v[218:225], v[44:47], v186, v187 op_sel_hi:[0,0,0]
	v_mfma_scale_f32_16x16x128_f8f6f4 v[40:43], v[8:15], v[218:225], v[40:43], v186, v187 op_sel_hi:[0,0,0]
	s_nop 0
	s_nop 0
	v_mfma_scale_f32_16x16x128_f8f6f4 v[84:87], v[16:23], v[194:201], v[84:87], v186, v187 op_sel_hi:[0,0,0]
	v_mfma_scale_f32_16x16x128_f8f6f4 v[80:83], v[24:31], v[194:201], v[80:83], v186, v187 op_sel_hi:[0,0,0]
	v_mfma_scale_f32_16x16x128_f8f6f4 v[68:71], v[16:23], v[202:209], v[68:71], v186, v187 op_sel_hi:[0,0,0]
	v_mfma_scale_f32_16x16x128_f8f6f4 v[64:67], v[24:31], v[202:209], v[64:67], v186, v187 op_sel_hi:[0,0,0]
	v_mfma_scale_f32_16x16x128_f8f6f4 v[52:55], v[16:23], v[210:217], v[52:55], v186, v187 op_sel_hi:[0,0,0]
	v_mfma_scale_f32_16x16x128_f8f6f4 v[48:51], v[24:31], v[210:217], v[48:51], v186, v187 op_sel_hi:[0,0,0]
	v_mfma_scale_f32_16x16x128_f8f6f4 v[36:39], v[16:23], v[218:225], v[36:39], v186, v187 op_sel_hi:[0,0,0]
	v_mfma_scale_f32_16x16x128_f8f6f4 v[32:35], v[24:31], v[218:225], v[32:35], v186, v187 op_sel_hi:[0,0,0]
	s_nop 0
	s_barrier
	s_add_i32 s66, s66, 2
	s_add_u32 s48, s48, 0x100
	s_addc_u32 s49, s49, 0
	s_add_u32 s64, s64, 0x100
	s_addc_u32 s65, s65, 0
	s_cmp_gt_u32 s66, 61
	s_cbranch_scc0 .LBB0_1195
	s_setprio 0
	s_nop 0
	s_and_b64 vcc, exec, s[12:13]
	s_cbranch_vccz .LBB0_1198
	s_barrier
